# HGRN2 prep epilogue: f32 division k=(1-lb)/(1+e^fz) as v_rcp_f32*mul and log f as v_log_f32*ln2 (f32, about 1 ulp; results are rounded to bf16 right after) instead of the IEEE/extended expansions; on
# speedup vs baseline: 1.0076x; 1.0036x over previous
; __device__ __forceinline__ unsigned cvt_pk_bf16(float lo, float hi) { unsigned r; asm volatile("v_cvt_pk_bf16_f32 %0, %1, %2" : "=v"(r) : "v"(lo), "v"(hi)); return r; }
; __device__ __forceinline__ float row_scan16(float v) { v += dpp_shr0<0x111>(v); v += dpp_shr0<0x112>(v); v += dpp_shr0<0x114>(v); v += dpp_shr0<0x118>(v); return v; }
; __device__ __forceinline__ float row_last16(float v, int lane) { return __builtin_bit_cast(float, __builtin_amdgcn_ds_bpermute((lane | 15) << 2, __builtin_bit_cast(int, v))); }
;     __device__ __forceinline__ void operator()(const f32x4 (&acc)[2][2][4][2], const Unit& u, int wr, int wc, int fr, int fq) const {
;     ...
;         for (int n = 0; n < 2; ++n) { const f32x4 l = *(const f32x4*)(lb + colh + 4 * n); om[n] = 1.0f - l; }
; #pragma unroll
;         for (int ai = 0; ai < 2; ++ai)
; #pragma unroll
;             for (int mp = 0; mp < 2; ++mp) {
;                 const int rowa = u.pm * BM + ai * HALF + wr * 64 + mp * 32 + fr;
;                 const int g = rowa >> 5;
;                 float qi[2][8], ki[2][8]; bf16_t* kot = KOT + ((size_t)g * 1024 + colh) * 32 + fr;
;                 float dec[8];
; #pragma unroll
;                 for (int n = 0; n < 2; ++n)
; #pragma unroll
;                     for (int q = 0; q < 4; ++q) { const int j = 4 * n + q;
;                         const float k0 = om[n][q] / (1.0f + __expf(acc[ai][1][2 * mp][n][q])), k1 = om[n][q] / (1.0f + __expf(acc[ai][1][2 * mp + 1][n][q]));
;                         const float p0 = row_scan16(__logf(1.0f - k0)); const float t0 = row_last16(p0, lane);
;                         const float p1 = row_scan16(__logf(1.0f - k1)) + t0; const float bl = row_last16(p1, lane);
;                         const float e0 = __expf(p0), e1 = __expf(p1);
;                         qi[0][j] = acc[ai][0][2 * mp][n][q] * e0; qi[1][j] = acc[ai][0][2 * mp + 1][n][q] * e1;
;                         ki[0][j] = k0 * __expf(-p0); ki[1][j] = k1 * __expf(-p1);
;                         kot[(size_t)j * 32] = (bf16_t)cvt_pk_bf16(k0 * __expf(bl - p0), 0.f); kot[(size_t)j * 32 + 16] = (bf16_t)cvt_pk_bf16(k1 * __expf(bl - p1), 0.f);
;                         dec[j] = __expf(bl); }
.LBB0_1145:
	v_lshl_or_b32 v158, s30, 7, v165
	v_ashrrev_i32_e32 v159, 31, v158
	v_lshl_add_u64 v[130:131], v[158:159], 2, s[16:17]
	global_load_dwordx4 v[134:137], v[130:131], off
	s_nop 0
	global_load_dwordx4 v[130:133], v[130:131], off offset:16
	v_mul_f32_e32 v146, 0x3fb8aa3b, v114
	v_mul_f32_e32 v170, 0x3fb8aa3b, v99
	v_mul_f32_e32 v160, 0x3fb8aa3b, v98
	v_exp_f32_e32 v146, v146
	v_exp_f32_e32 v170, v170
	s_lshl_b32 s2, s28, 8
	v_mul_f32_e32 v161, 0x3fb8aa3b, v115
	v_exp_f32_e32 v171, v160
	s_add_i32 s2, s2, s54
	v_exp_f32_e32 v172, v161
	s_ashr_i32 s0, s2, 5
	s_ashr_i32 s1, s0, 31
	v_add_f32_e32 v173, 1.0, v146
	v_add_f32_e32 v175, 1.0, v170
	s_lshl_b64 s[38:39], s[0:1], 10
	v_add_f32_e32 v171, 1.0, v171
	v_add_f32_e32 v174, 1.0, v172
	v_lshl_add_u64 v[160:161], s[38:39], 0, v[158:159]
	v_lshlrev_b64 v[160:161], 6, v[160:161]
	v_lshl_add_u64 v[160:161], v[148:149], 0, v[160:161]
	v_mul_f32_e32 v190, 0x3fb8aa3b, v101
	v_exp_f32_e32 v190, v190
	v_mul_f32_e32 v195, 0x3fb8aa3b, v90
	v_exp_f32_e32 v195, v195
	v_mul_f32_e32 v200, 0x3fb8aa3b, v91
	v_exp_f32_e32 v200, v200
	v_mul_f32_e32 v205, 0x3fb8aa3b, v92
	v_exp_f32_e32 v205, v205
	s_waitcnt vmcnt(0)
	v_sub_f32_e32 v170, 1.0, v134
	v_sub_f32_e32 v146, 1.0, v135
	v_sub_f32_e32 v135, 1.0, v130
	v_sub_f32_e32 v134, 1.0, v131
	v_rcp_f32_e32 v130, v173
	s_nop 0
	v_mul_f32_e32 v177, v170, v130
	v_rcp_f32_e32 v130, v171
	s_nop 0
	v_mul_f32_e32 v178, v170, v130
	v_sub_f32_e32 v130, 1.0, v177
	v_sub_f32_e32 v171, 1.0, v178
	v_log_f32_e32 v130, v130
	v_sub_f32_e32 v136, 1.0, v136
	v_log_f32_e32 v171, v171
	v_mul_f32_e32 v130, 0x3f317218, v130
	v_sub_f32_e32 v137, 1.0, v137
	s_nop 0
	v_add_f32_dpp v130, v130, v130 row_shr:1 row_mask:0xf bank_mask:0xf bound_ctrl:1
	v_mul_f32_e32 v131, 0x3f317218, v171
	s_nop 0
	v_add_f32_dpp v130, v130, v130 row_shr:2 row_mask:0xf bank_mask:0xf bound_ctrl:1
	v_add_f32_dpp v131, v131, v131 row_shr:1 row_mask:0xf bank_mask:0xf bound_ctrl:1
	s_nop 0
	v_add_f32_dpp v130, v130, v130 row_shr:4 row_mask:0xf bank_mask:0xf bound_ctrl:1
	v_add_f32_dpp v131, v131, v131 row_shr:2 row_mask:0xf bank_mask:0xf bound_ctrl:1
	s_nop 0
	v_add_f32_dpp v171, v130, v130 row_shr:8 row_mask:0xf bank_mask:0xf bound_ctrl:1
	v_mul_f32_e32 v172, 0x3fb8aa3b, v171
	v_add_f32_dpp v130, v131, v131 row_shr:4 row_mask:0xf bank_mask:0xf bound_ctrl:1
	ds_bpermute_b32 v131, v162, v171
	v_mul_f32_e32 v173, 0xbfb8aa3b, v171
	v_add_f32_dpp v130, v130, v130 row_shr:8 row_mask:0xf bank_mask:0xf bound_ctrl:1
	v_exp_f32_e32 v172, v172
	v_exp_f32_e32 v179, v173
	s_waitcnt lgkmcnt(0)
	v_add_f32_e32 v131, v130, v131
	ds_bpermute_b32 v130, v162, v131
	v_mul_f32_e32 v173, v126, v172
	v_mul_f32_e32 v172, v177, v179
	v_mul_f32_e32 v179, 0x3fb8aa3b, v131
	v_mul_f32_e32 v180, 0xbfb8aa3b, v131
	s_waitcnt lgkmcnt(0)
	v_sub_f32_e32 v171, v130, v171
	v_mul_f32_e32 v171, 0x3fb8aa3b, v171
	v_sub_f32_e32 v131, v130, v131
	v_exp_f32_e32 v183, v171
	v_mul_f32_e32 v131, 0x3fb8aa3b, v131
	v_exp_f32_e32 v180, v180
	v_exp_f32_e32 v184, v131
	v_mul_f32_e32 v177, v177, v183
	v_cvt_pk_bf16_f32 v177, v177, v147
	v_mul_f32_e32 v131, v178, v180
	v_mul_f32_e32 v178, v178, v184
	global_store_short v[160:161], v177, off
	v_cvt_pk_bf16_f32 v177, v178, v147
	v_exp_f32_e32 v179, v179
	global_store_short v[160:161], v177, off offset:32
	v_mul_f32_e32 v184, 0x3fb8aa3b, v100
	v_mul_f32_e32 v171, v118, v179
	v_rcp_f32_e32 v176, v174
	s_nop 0
	v_mul_f32_e32 v179, v146, v176
	v_sub_f32_e32 v178, 1.0, v179
	v_log_f32_e32 v178, v178
	v_rcp_f32_e32 v174, v175
	s_nop 0
	v_mul_f32_e32 v180, v146, v174
	v_exp_f32_e32 v184, v184
	v_sub_f32_e32 v132, 1.0, v132
	v_sub_f32_e32 v133, 1.0, v133
	v_mul_f32_e32 v174, 0x3f317218, v178
	v_sub_f32_e32 v175, 1.0, v180
	s_nop 0
	v_add_f32_dpp v174, v174, v174 row_shr:1 row_mask:0xf bank_mask:0xf bound_ctrl:1
	s_nop 0
	v_log_f32_e32 v175, v175
	v_add_f32_dpp v174, v174, v174 row_shr:2 row_mask:0xf bank_mask:0xf bound_ctrl:1
	s_nop 1
	v_add_f32_dpp v174, v174, v174 row_shr:4 row_mask:0xf bank_mask:0xf bound_ctrl:1
	s_nop 1
	v_add_f32_dpp v176, v174, v174 row_shr:8 row_mask:0xf bank_mask:0xf bound_ctrl:1
	ds_bpermute_b32 v174, v162, v176
	v_mul_f32_e32 v175, 0x3f317218, v175
	s_nop 1
	v_add_f32_dpp v175, v175, v175 row_shr:1 row_mask:0xf bank_mask:0xf bound_ctrl:1
	s_nop 1
	v_add_f32_dpp v175, v175, v175 row_shr:2 row_mask:0xf bank_mask:0xf bound_ctrl:1
	s_nop 1
	v_add_f32_dpp v175, v175, v175 row_shr:4 row_mask:0xf bank_mask:0xf bound_ctrl:1
	s_nop 1
	v_add_f32_dpp v175, v175, v175 row_shr:8 row_mask:0xf bank_mask:0xf bound_ctrl:1
	s_waitcnt lgkmcnt(0)
	v_add_f32_e32 v181, v175, v174
	v_mul_f32_e32 v174, 0x3fb8aa3b, v176
	v_exp_f32_e32 v175, v174
	ds_bpermute_b32 v174, v162, v181
	v_mul_f32_e32 v177, 0x3fb8aa3b, v181
	v_exp_f32_e32 v178, v177
	v_mul_f32_e32 v177, v127, v175
	v_mul_f32_e32 v175, 0xbfb8aa3b, v176
	s_waitcnt lgkmcnt(0)
; __device__ __forceinline__ unsigned cvt_pk_bf16(float lo, float hi) { unsigned r; asm volatile("v_cvt_pk_bf16_f32 %0, %1, %2" : "=v"(r) : "v"(lo), "v"(hi)); return r; }
; __device__ __forceinline__ float row_scan16(float v) { v += dpp_shr0<0x111>(v); v += dpp_shr0<0x112>(v); v += dpp_shr0<0x114>(v); v += dpp_shr0<0x118>(v); return v; }
; __device__ __forceinline__ float row_last16(float v, int lane) { return __builtin_bit_cast(float, __builtin_amdgcn_ds_bpermute((lane | 15) << 2, __builtin_bit_cast(int, v))); }
;     __device__ __forceinline__ void operator()(const f32x4 (&acc)[2][2][4][2], const Unit& u, int wr, int wc, int fr, int fq) const {
;     ...
;                 for (int n = 0; n < 2; ++n)
; #pragma unroll
;                     for (int q = 0; q < 4; ++q) { const int j = 4 * n + q;
;                         const float k0 = om[n][q] / (1.0f + __expf(acc[ai][1][2 * mp][n][q])), k1 = om[n][q] / (1.0f + __expf(acc[ai][1][2 * mp + 1][n][q]));
;                         const float p0 = row_scan16(__logf(1.0f - k0)); const float t0 = row_last16(p0, lane);
;                         const float p1 = row_scan16(__logf(1.0f - k1)) + t0; const float bl = row_last16(p1, lane);
;                         const float e0 = __expf(p0), e1 = __expf(p1);
;                         qi[0][j] = acc[ai][0][2 * mp][n][q] * e0; qi[1][j] = acc[ai][0][2 * mp + 1][n][q] * e1;
;                         ki[0][j] = k0 * __expf(-p0); ki[1][j] = k1 * __expf(-p1);
;                         kot[(size_t)j * 32] = (bf16_t)cvt_pk_bf16(k0 * __expf(bl - p0), 0.f); kot[(size_t)j * 32 + 16] = (bf16_t)cvt_pk_bf16(k1 * __expf(bl - p1), 0.f);
;                         dec[j] = __expf(bl); }
	v_sub_f32_e32 v176, v174, v176
	v_mul_f32_e32 v176, 0x3fb8aa3b, v176
	v_exp_f32_e32 v175, v175
	v_exp_f32_e32 v183, v176
	v_mul_f32_e32 v176, v119, v178
	v_mul_f32_e32 v182, 0xbfb8aa3b, v181
	v_mul_f32_e32 v178, v179, v175
	v_mul_f32_e32 v179, v179, v183
	v_cvt_pk_bf16_f32 v179, v179, v147
	global_store_short v[160:161], v179, off offset:64
	v_mul_f32_e32 v179, 0x3fb8aa3b, v116
	v_exp_f32_e32 v179, v179
	v_exp_f32_e32 v182, v182
	v_sub_f32_e32 v181, v174, v181
	v_mul_f32_e32 v181, 0x3fb8aa3b, v181
	v_exp_f32_e32 v181, v181
	v_add_f32_e32 v179, 1.0, v179
	v_mul_f32_e32 v175, v180, v182
	v_mul_f32_e32 v180, v180, v181
	v_cvt_pk_bf16_f32 v180, v180, v147
	global_store_short v[160:161], v180, off offset:96
	v_add_f32_e32 v182, 1.0, v184
	v_rcp_f32_e32 v180, v179
	s_nop 0
	v_mul_f32_e32 v187, v136, v180
	v_sub_f32_e32 v181, 1.0, v187
	v_log_f32_e32 v181, v181
	v_rcp_f32_e32 v179, v182
	s_nop 0
	v_mul_f32_e32 v184, v136, v179
	s_nop 1
	v_mul_f32_e32 v179, 0x3f317218, v181
	v_sub_f32_e32 v180, 1.0, v184
	s_nop 0
	v_add_f32_dpp v179, v179, v179 row_shr:1 row_mask:0xf bank_mask:0xf bound_ctrl:1
	s_nop 0
	v_log_f32_e32 v180, v180
	v_add_f32_dpp v179, v179, v179 row_shr:2 row_mask:0xf bank_mask:0xf bound_ctrl:1
	s_nop 1
	v_add_f32_dpp v179, v179, v179 row_shr:4 row_mask:0xf bank_mask:0xf bound_ctrl:1
	s_nop 1
	v_add_f32_dpp v181, v179, v179 row_shr:8 row_mask:0xf bank_mask:0xf bound_ctrl:1
	ds_bpermute_b32 v179, v162, v181
	v_mul_f32_e32 v180, 0x3f317218, v180
	s_nop 1
	v_add_f32_dpp v180, v180, v180 row_shr:1 row_mask:0xf bank_mask:0xf bound_ctrl:1
	s_nop 1
	v_add_f32_dpp v180, v180, v180 row_shr:2 row_mask:0xf bank_mask:0xf bound_ctrl:1
	s_nop 1
	v_add_f32_dpp v180, v180, v180 row_shr:4 row_mask:0xf bank_mask:0xf bound_ctrl:1
	s_nop 1
	v_add_f32_dpp v180, v180, v180 row_shr:8 row_mask:0xf bank_mask:0xf bound_ctrl:1
	s_waitcnt lgkmcnt(0)
	v_add_f32_e32 v185, v180, v179
	v_mul_f32_e32 v179, 0x3fb8aa3b, v181
	v_exp_f32_e32 v180, v179
	ds_bpermute_b32 v179, v162, v185
	v_mul_f32_e32 v182, 0x3fb8aa3b, v185
	v_exp_f32_e32 v183, v182
	v_mul_f32_e32 v182, v128, v180
	v_mul_f32_e32 v180, 0xbfb8aa3b, v181
	s_waitcnt lgkmcnt(0)
	v_sub_f32_e32 v181, v179, v181
	v_mul_f32_e32 v181, 0x3fb8aa3b, v181
	v_exp_f32_e32 v180, v180
	v_exp_f32_e32 v189, v181
	v_mul_f32_e32 v181, v120, v183
	v_mul_f32_e32 v188, 0xbfb8aa3b, v185
	v_mul_f32_e32 v183, v187, v180
	v_mul_f32_e32 v187, v187, v189
	v_cvt_pk_bf16_f32 v187, v187, v147
	global_store_short v[160:161], v187, off offset:128
	v_mul_f32_e32 v187, 0x3fb8aa3b, v117
	v_exp_f32_e32 v187, v187
	v_exp_f32_e32 v188, v188
	v_sub_f32_e32 v185, v179, v185
	v_mul_f32_e32 v185, 0x3fb8aa3b, v185
	v_exp_f32_e32 v185, v185
	v_add_f32_e32 v187, 1.0, v187
	v_mul_f32_e32 v180, v184, v188
	v_mul_f32_e32 v184, v184, v185
	v_cvt_pk_bf16_f32 v184, v184, v147
	global_store_short v[160:161], v184, off offset:160
	v_add_f32_e32 v188, 1.0, v190
	v_rcp_f32_e32 v184, v187
	s_nop 0
	v_mul_f32_e32 v192, v137, v184
	v_sub_f32_e32 v187, 1.0, v192
	v_log_f32_e32 v187, v187
	v_rcp_f32_e32 v184, v188
	s_nop 0
	v_mul_f32_e32 v190, v137, v184
	s_nop 1
	v_mul_f32_e32 v184, 0x3f317218, v187
	v_sub_f32_e32 v185, 1.0, v190
	s_nop 0
	v_add_f32_dpp v184, v184, v184 row_shr:1 row_mask:0xf bank_mask:0xf bound_ctrl:1
	s_nop 0
	v_log_f32_e32 v185, v185
	v_add_f32_dpp v184, v184, v184 row_shr:2 row_mask:0xf bank_mask:0xf bound_ctrl:1
	s_nop 1
	v_add_f32_dpp v184, v184, v184 row_shr:4 row_mask:0xf bank_mask:0xf bound_ctrl:1
	s_nop 1
	v_add_f32_dpp v187, v184, v184 row_shr:8 row_mask:0xf bank_mask:0xf bound_ctrl:1
	ds_bpermute_b32 v184, v162, v187
	v_mul_f32_e32 v185, 0x3f317218, v185
	s_nop 1
	v_add_f32_dpp v185, v185, v185 row_shr:1 row_mask:0xf bank_mask:0xf bound_ctrl:1
	s_nop 1
	v_add_f32_dpp v185, v185, v185 row_shr:2 row_mask:0xf bank_mask:0xf bound_ctrl:1
	s_nop 1
	v_add_f32_dpp v185, v185, v185 row_shr:4 row_mask:0xf bank_mask:0xf bound_ctrl:1
	s_nop 1
	v_add_f32_dpp v185, v185, v185 row_shr:8 row_mask:0xf bank_mask:0xf bound_ctrl:1
	s_waitcnt lgkmcnt(0)
	v_add_f32_e32 v191, v185, v184
	v_mul_f32_e32 v184, 0x3fb8aa3b, v187
	v_exp_f32_e32 v185, v184
	ds_bpermute_b32 v184, v162, v191
	v_mul_f32_e32 v188, 0x3fb8aa3b, v191
	v_exp_f32_e32 v189, v188
	v_mul_f32_e32 v188, v129, v185
	v_mul_f32_e32 v185, 0xbfb8aa3b, v187
	s_waitcnt lgkmcnt(0)
	v_sub_f32_e32 v187, v184, v187
	v_mul_f32_e32 v187, 0x3fb8aa3b, v187
	v_exp_f32_e32 v185, v185
	v_exp_f32_e32 v194, v187
	v_mul_f32_e32 v187, v121, v189
	v_mul_f32_e32 v193, 0xbfb8aa3b, v191
	v_mul_f32_e32 v189, v192, v185
	v_mul_f32_e32 v192, v192, v194
	v_cvt_pk_bf16_f32 v192, v192, v147
	global_store_short v[160:161], v192, off offset:192
	v_mul_f32_e32 v192, 0x3fb8aa3b, v106
	v_exp_f32_e32 v192, v192
	v_exp_f32_e32 v193, v193
	v_sub_f32_e32 v191, v184, v191
	v_mul_f32_e32 v191, 0x3fb8aa3b, v191
	v_exp_f32_e32 v191, v191
	v_add_f32_e32 v192, 1.0, v192
	v_mul_f32_e32 v185, v190, v193
	v_mul_f32_e32 v190, v190, v191
	v_cvt_pk_bf16_f32 v190, v190, v147
	global_store_short v[160:161], v190, off offset:224
	v_add_f32_e32 v193, 1.0, v195
	v_rcp_f32_e32 v190, v192
	s_nop 0
	v_mul_f32_e32 v197, v135, v190
	v_sub_f32_e32 v192, 1.0, v197
	v_log_f32_e32 v192, v192
	v_rcp_f32_e32 v190, v193
	s_nop 0
	v_mul_f32_e32 v195, v135, v190
	s_nop 1
	v_mul_f32_e32 v190, 0x3f317218, v192
	v_sub_f32_e32 v191, 1.0, v195
	s_nop 0
	v_add_f32_dpp v190, v190, v190 row_shr:1 row_mask:0xf bank_mask:0xf bound_ctrl:1
	s_nop 0
	v_log_f32_e32 v191, v191
	v_add_f32_dpp v190, v190, v190 row_shr:2 row_mask:0xf bank_mask:0xf bound_ctrl:1
	s_nop 1
	v_add_f32_dpp v190, v190, v190 row_shr:4 row_mask:0xf bank_mask:0xf bound_ctrl:1
	s_nop 1
	v_add_f32_dpp v192, v190, v190 row_shr:8 row_mask:0xf bank_mask:0xf bound_ctrl:1
	ds_bpermute_b32 v190, v162, v192
	v_mul_f32_e32 v191, 0x3f317218, v191
	s_nop 1
	v_add_f32_dpp v191, v191, v191 row_shr:1 row_mask:0xf bank_mask:0xf bound_ctrl:1
	s_nop 1
	v_add_f32_dpp v191, v191, v191 row_shr:2 row_mask:0xf bank_mask:0xf bound_ctrl:1
	s_nop 1
	v_add_f32_dpp v191, v191, v191 row_shr:4 row_mask:0xf bank_mask:0xf bound_ctrl:1
	s_nop 1
	v_add_f32_dpp v191, v191, v191 row_shr:8 row_mask:0xf bank_mask:0xf bound_ctrl:1
	s_waitcnt lgkmcnt(0)
; __device__ __forceinline__ unsigned cvt_pk_bf16(float lo, float hi) { unsigned r; asm volatile("v_cvt_pk_bf16_f32 %0, %1, %2" : "=v"(r) : "v"(lo), "v"(hi)); return r; }
; __device__ __forceinline__ float row_scan16(float v) { v += dpp_shr0<0x111>(v); v += dpp_shr0<0x112>(v); v += dpp_shr0<0x114>(v); v += dpp_shr0<0x118>(v); return v; }
; __device__ __forceinline__ float row_last16(float v, int lane) { return __builtin_bit_cast(float, __builtin_amdgcn_ds_bpermute((lane | 15) << 2, __builtin_bit_cast(int, v))); }
;     __device__ __forceinline__ void operator()(const f32x4 (&acc)[2][2][4][2], const Unit& u, int wr, int wc, int fr, int fq) const {
;     ...
;                 for (int n = 0; n < 2; ++n)
; #pragma unroll
;                     for (int q = 0; q < 4; ++q) { const int j = 4 * n + q;
;                         const float k0 = om[n][q] / (1.0f + __expf(acc[ai][1][2 * mp][n][q])), k1 = om[n][q] / (1.0f + __expf(acc[ai][1][2 * mp + 1][n][q]));
;                         const float p0 = row_scan16(__logf(1.0f - k0)); const float t0 = row_last16(p0, lane);
;                         const float p1 = row_scan16(__logf(1.0f - k1)) + t0; const float bl = row_last16(p1, lane);
;                         const float e0 = __expf(p0), e1 = __expf(p1);
;                         qi[0][j] = acc[ai][0][2 * mp][n][q] * e0; qi[1][j] = acc[ai][0][2 * mp + 1][n][q] * e1;
;                         ki[0][j] = k0 * __expf(-p0); ki[1][j] = k1 * __expf(-p1);
;                         kot[(size_t)j * 32] = (bf16_t)cvt_pk_bf16(k0 * __expf(bl - p0), 0.f); kot[(size_t)j * 32 + 16] = (bf16_t)cvt_pk_bf16(k1 * __expf(bl - p1), 0.f);
;                         dec[j] = __expf(bl); }
	v_add_f32_e32 v196, v191, v190
	v_mul_f32_e32 v190, 0x3fb8aa3b, v192
	v_exp_f32_e32 v191, v190
	ds_bpermute_b32 v190, v162, v196
	v_mul_f32_e32 v193, 0x3fb8aa3b, v196
	v_exp_f32_e32 v194, v193
	v_mul_f32_e32 v193, v122, v191
	v_mul_f32_e32 v191, 0xbfb8aa3b, v192
	s_waitcnt lgkmcnt(0)
	v_sub_f32_e32 v192, v190, v192
	v_mul_f32_e32 v192, 0x3fb8aa3b, v192
	v_exp_f32_e32 v191, v191
	v_exp_f32_e32 v199, v192
	v_mul_f32_e32 v192, v110, v194
	v_mul_f32_e32 v198, 0xbfb8aa3b, v196
	v_mul_f32_e32 v194, v197, v191
	v_mul_f32_e32 v197, v197, v199
	v_cvt_pk_bf16_f32 v197, v197, v147
	global_store_short v[160:161], v197, off offset:256
	v_mul_f32_e32 v197, 0x3fb8aa3b, v107
	v_exp_f32_e32 v197, v197
	v_exp_f32_e32 v198, v198
	v_sub_f32_e32 v196, v190, v196
	v_mul_f32_e32 v196, 0x3fb8aa3b, v196
	v_exp_f32_e32 v196, v196
	v_add_f32_e32 v197, 1.0, v197
	v_mul_f32_e32 v191, v195, v198
	v_mul_f32_e32 v195, v195, v196
	v_cvt_pk_bf16_f32 v195, v195, v147
	global_store_short v[160:161], v195, off offset:288
	v_add_f32_e32 v198, 1.0, v200
	v_rcp_f32_e32 v195, v197
	s_nop 0
	v_mul_f32_e32 v202, v134, v195
	v_sub_f32_e32 v197, 1.0, v202
	v_log_f32_e32 v197, v197
	v_rcp_f32_e32 v195, v198
	s_nop 0
	v_mul_f32_e32 v200, v134, v195
	s_nop 1
	v_mul_f32_e32 v195, 0x3f317218, v197
	v_sub_f32_e32 v196, 1.0, v200
	s_nop 0
	v_add_f32_dpp v195, v195, v195 row_shr:1 row_mask:0xf bank_mask:0xf bound_ctrl:1
	s_nop 0
	v_log_f32_e32 v196, v196
	v_add_f32_dpp v195, v195, v195 row_shr:2 row_mask:0xf bank_mask:0xf bound_ctrl:1
	s_nop 1
	v_add_f32_dpp v195, v195, v195 row_shr:4 row_mask:0xf bank_mask:0xf bound_ctrl:1
	s_nop 1
	v_add_f32_dpp v197, v195, v195 row_shr:8 row_mask:0xf bank_mask:0xf bound_ctrl:1
	ds_bpermute_b32 v195, v162, v197
	v_mul_f32_e32 v196, 0x3f317218, v196
	s_nop 1
	v_add_f32_dpp v196, v196, v196 row_shr:1 row_mask:0xf bank_mask:0xf bound_ctrl:1
	s_nop 1
	v_add_f32_dpp v196, v196, v196 row_shr:2 row_mask:0xf bank_mask:0xf bound_ctrl:1
	s_nop 1
	v_add_f32_dpp v196, v196, v196 row_shr:4 row_mask:0xf bank_mask:0xf bound_ctrl:1
	s_nop 1
	v_add_f32_dpp v196, v196, v196 row_shr:8 row_mask:0xf bank_mask:0xf bound_ctrl:1
	s_waitcnt lgkmcnt(0)
	v_add_f32_e32 v201, v196, v195
	v_mul_f32_e32 v195, 0x3fb8aa3b, v197
	v_exp_f32_e32 v196, v195
	ds_bpermute_b32 v195, v162, v201
	v_mul_f32_e32 v198, 0x3fb8aa3b, v201
	v_exp_f32_e32 v199, v198
	v_mul_f32_e32 v198, v123, v196
	v_mul_f32_e32 v196, 0xbfb8aa3b, v197
	s_waitcnt lgkmcnt(0)
	v_sub_f32_e32 v197, v195, v197
	v_mul_f32_e32 v197, 0x3fb8aa3b, v197
	v_exp_f32_e32 v196, v196
	v_exp_f32_e32 v204, v197
	v_mul_f32_e32 v197, v111, v199
	v_mul_f32_e32 v203, 0xbfb8aa3b, v201
	v_mul_f32_e32 v199, v202, v196
	v_mul_f32_e32 v202, v202, v204
	v_cvt_pk_bf16_f32 v202, v202, v147
	global_store_short v[160:161], v202, off offset:320
	v_mul_f32_e32 v202, 0x3fb8aa3b, v108
	v_exp_f32_e32 v202, v202
	v_exp_f32_e32 v203, v203
	v_sub_f32_e32 v201, v195, v201
	v_mul_f32_e32 v201, 0x3fb8aa3b, v201
	v_exp_f32_e32 v201, v201
	v_add_f32_e32 v202, 1.0, v202
	v_mul_f32_e32 v196, v200, v203
	v_mul_f32_e32 v200, v200, v201
	v_cvt_pk_bf16_f32 v200, v200, v147
	global_store_short v[160:161], v200, off offset:352
	v_add_f32_e32 v203, 1.0, v205
	v_rcp_f32_e32 v200, v202
	s_nop 0
	v_mul_f32_e32 v201, v132, v200
	v_sub_f32_e32 v204, 1.0, v201
	v_log_f32_e32 v204, v204
	v_rcp_f32_e32 v200, v203
	s_nop 0
	v_mul_f32_e32 v202, v132, v200
	s_nop 1
	v_mul_f32_e32 v200, 0x3f317218, v204
	v_sub_f32_e32 v203, 1.0, v202
	s_nop 0
	v_add_f32_dpp v200, v200, v200 row_shr:1 row_mask:0xf bank_mask:0xf bound_ctrl:1
	s_nop 0
	v_log_f32_e32 v203, v203
	v_add_f32_dpp v200, v200, v200 row_shr:2 row_mask:0xf bank_mask:0xf bound_ctrl:1
	s_nop 1
	v_add_f32_dpp v200, v200, v200 row_shr:4 row_mask:0xf bank_mask:0xf bound_ctrl:1
	s_nop 1
	v_add_f32_dpp v204, v200, v200 row_shr:8 row_mask:0xf bank_mask:0xf bound_ctrl:1
	ds_bpermute_b32 v200, v162, v204
	v_mul_f32_e32 v203, 0x3f317218, v203
	v_mul_f32_e32 v207, 0xbfb8aa3b, v204
	v_exp_f32_e32 v207, v207
	v_add_f32_dpp v203, v203, v203 row_shr:1 row_mask:0xf bank_mask:0xf bound_ctrl:1
	v_mul_f32_e32 v211, v201, v207
	s_nop 0
	v_add_f32_dpp v203, v203, v203 row_shr:2 row_mask:0xf bank_mask:0xf bound_ctrl:1
	v_mul_f32_e32 v207, 0x3fb8aa3b, v93
	v_exp_f32_e32 v207, v207
	v_add_f32_dpp v203, v203, v203 row_shr:4 row_mask:0xf bank_mask:0xf bound_ctrl:1
	s_nop 1
	v_add_f32_dpp v203, v203, v203 row_shr:8 row_mask:0xf bank_mask:0xf bound_ctrl:1
	s_waitcnt lgkmcnt(0)
	v_add_f32_e32 v203, v203, v200
	v_mul_f32_e32 v200, 0x3fb8aa3b, v204
	v_exp_f32_e32 v205, v200
	ds_bpermute_b32 v200, v162, v203
	v_mul_f32_e32 v206, 0x3fb8aa3b, v203
	v_exp_f32_e32 v206, v206
	v_mul_f32_e32 v208, 0xbfb8aa3b, v203
	v_exp_f32_e32 v208, v208
	s_waitcnt lgkmcnt(0)
; __device__ __forceinline__ unsigned cvt_pk_bf16(float lo, float hi) { unsigned r; asm volatile("v_cvt_pk_bf16_f32 %0, %1, %2" : "=v"(r) : "v"(lo), "v"(hi)); return r; }
; __device__ __forceinline__ float row_scan16(float v) { v += dpp_shr0<0x111>(v); v += dpp_shr0<0x112>(v); v += dpp_shr0<0x114>(v); v += dpp_shr0<0x118>(v); return v; }
; __device__ __forceinline__ float row_last16(float v, int lane) { return __builtin_bit_cast(float, __builtin_amdgcn_ds_bpermute((lane | 15) << 2, __builtin_bit_cast(int, v))); }
;     __device__ __forceinline__ void operator()(const f32x4 (&acc)[2][2][4][2], const Unit& u, int wr, int wc, int fr, int fq) const {
;     ...
;                         const float k0 = om[n][q] / (1.0f + __expf(acc[ai][1][2 * mp][n][q])), k1 = om[n][q] / (1.0f + __expf(acc[ai][1][2 * mp + 1][n][q]));
;                         const float p0 = row_scan16(__logf(1.0f - k0)); const float t0 = row_last16(p0, lane);
;                         const float p1 = row_scan16(__logf(1.0f - k1)) + t0; const float bl = row_last16(p1, lane);
;                         const float e0 = __expf(p0), e1 = __expf(p1);
;                         qi[0][j] = acc[ai][0][2 * mp][n][q] * e0; qi[1][j] = acc[ai][0][2 * mp + 1][n][q] * e1;
;                         ki[0][j] = k0 * __expf(-p0); ki[1][j] = k1 * __expf(-p1);
;                         kot[(size_t)j * 32] = (bf16_t)cvt_pk_bf16(k0 * __expf(bl - p0), 0.f); kot[(size_t)j * 32 + 16] = (bf16_t)cvt_pk_bf16(k1 * __expf(bl - p1), 0.f);
;                         dec[j] = __expf(bl); }
; #pragma unroll
;                 for (int mm = 0; mm < 2; ++mm) { const size_t ro = (size_t)(rowa + 16 * mm) * 1024 + colh;
;                     u32x4 w; w.x = cvt_pk_bf16(qi[mm][0], qi[mm][1]); w.y = cvt_pk_bf16(qi[mm][2], qi[mm][3]); w.z = cvt_pk_bf16(qi[mm][4], qi[mm][5]); w.w = cvt_pk_bf16(qi[mm][6], qi[mm][7]);
;                     *(u32x4*)(CQ + ro) = w;
;                     w.x = cvt_pk_bf16(ki[mm][0], ki[mm][1]); w.y = cvt_pk_bf16(ki[mm][2], ki[mm][3]); w.z = cvt_pk_bf16(ki[mm][4], ki[mm][5]); w.w = cvt_pk_bf16(ki[mm][6], ki[mm][7]);
;                     *(u32x4*)(CK + ro) = w; }
;                 if (fr == 15) { float* dp = DEC + (size_t)g * 1024 + colh; *(f32x4*)dp = (f32x4){dec[0], dec[1], dec[2], dec[3]}; *(f32x4*)(dp + 4) = (f32x4){dec[4], dec[5], dec[6], dec[7]}; }
	v_sub_f32_e32 v204, v200, v204
	v_mul_f32_e32 v204, 0x3fb8aa3b, v204
	v_exp_f32_e32 v204, v204
	v_sub_f32_e32 v203, v200, v203
	v_mul_f32_e32 v203, 0x3fb8aa3b, v203
	v_exp_f32_e32 v203, v203
	v_mul_f32_e32 v201, v201, v204
	v_cvt_pk_bf16_f32 v201, v201, v147
	global_store_short v[160:161], v201, off offset:384
	v_mul_f32_e32 v201, 0x3fb8aa3b, v109
	v_exp_f32_e32 v201, v201
	v_mul_f32_e32 v210, v112, v206
	v_mul_f32_e32 v212, v202, v208
	v_mul_f32_e32 v202, v202, v203
	v_add_f32_e32 v201, 1.0, v201
	v_cvt_pk_bf16_f32 v202, v202, v147
	global_store_short v[160:161], v202, off offset:416
	v_mul_f32_e32 v205, v124, v205
	v_add_f32_e32 v204, 1.0, v207
	v_rcp_f32_e32 v202, v201
	s_nop 0
	v_mul_f32_e32 v202, v133, v202
	v_sub_f32_e32 v206, 1.0, v202
	v_log_f32_e32 v206, v206
	v_rcp_f32_e32 v201, v204
	s_nop 0
	v_mul_f32_e32 v203, v133, v201
	s_nop 1
	v_mul_f32_e32 v201, 0x3f317218, v206
	v_sub_f32_e32 v204, 1.0, v203
	s_nop 0
	v_add_f32_dpp v201, v201, v201 row_shr:1 row_mask:0xf bank_mask:0xf bound_ctrl:1
	s_nop 0
	v_log_f32_e32 v204, v204
	v_add_f32_dpp v201, v201, v201 row_shr:2 row_mask:0xf bank_mask:0xf bound_ctrl:1
	s_nop 1
	v_add_f32_dpp v201, v201, v201 row_shr:4 row_mask:0xf bank_mask:0xf bound_ctrl:1
	s_nop 1
	v_add_f32_dpp v206, v201, v201 row_shr:8 row_mask:0xf bank_mask:0xf bound_ctrl:1
	ds_bpermute_b32 v201, v162, v206
	v_mul_f32_e32 v204, 0x3f317218, v204
	v_mul_f32_e32 v207, 0x3fb8aa3b, v206
	v_mul_f32_e32 v209, 0xbfb8aa3b, v206
	v_add_f32_dpp v204, v204, v204 row_shr:1 row_mask:0xf bank_mask:0xf bound_ctrl:1
	v_exp_f32_e32 v209, v209
	v_exp_f32_e32 v207, v207
	v_add_f32_dpp v204, v204, v204 row_shr:2 row_mask:0xf bank_mask:0xf bound_ctrl:1
	v_mul_f32_e32 v216, v202, v209
	s_nop 0
	v_add_f32_dpp v204, v204, v204 row_shr:4 row_mask:0xf bank_mask:0xf bound_ctrl:1
	v_mul_f32_e32 v214, v125, v207
	s_nop 0
	v_add_f32_dpp v204, v204, v204 row_shr:8 row_mask:0xf bank_mask:0xf bound_ctrl:1
	s_waitcnt lgkmcnt(0)
	v_add_f32_e32 v204, v204, v201
	ds_bpermute_b32 v201, v162, v204
	v_mul_f32_e32 v208, 0x3fb8aa3b, v204
	v_mul_f32_e32 v213, 0xbfb8aa3b, v204
	v_exp_f32_e32 v213, v213
	v_exp_f32_e32 v208, v208
	s_waitcnt lgkmcnt(0)
	v_sub_f32_e32 v206, v201, v206
	v_mul_f32_e32 v206, 0x3fb8aa3b, v206
	v_exp_f32_e32 v206, v206
	v_sub_f32_e32 v204, v201, v204
	v_mul_f32_e32 v204, 0x3fb8aa3b, v204
	v_exp_f32_e32 v204, v204
	v_mul_f32_e32 v202, v202, v206
	v_cvt_pk_bf16_f32 v202, v202, v147
	global_store_short v[160:161], v202, off offset:448
	v_mul_f32_e32 v202, v203, v204
	v_cvt_pk_bf16_f32 v202, v202, v147
	global_store_short v[160:161], v202, off offset:480
	v_or_b32_e32 v160, s2, v1
	v_ashrrev_i32_e32 v161, 31, v160
	v_mul_f32_e32 v213, v203, v213
	v_lshlrev_b64 v[202:203], 10, v[160:161]
	v_or_b32_e32 v160, 16, v160
	v_lshl_add_u64 v[206:207], v[202:203], 0, v[158:159]
	v_ashrrev_i32_e32 v161, 31, v160
	v_lshlrev_b64 v[206:207], 1, v[206:207]
	v_lshlrev_b64 v[160:161], 10, v[160:161]
	v_mul_f32_e32 v215, v113, v208
	v_cvt_pk_bf16_f32 v202, v173, v177
	v_cvt_pk_bf16_f32 v203, v182, v188
	v_cvt_pk_bf16_f32 v204, v193, v198
	v_cvt_pk_bf16_f32 v205, v205, v214
	v_lshl_add_u64 v[208:209], s[64:65], 0, v[206:207]
	v_lshl_add_u64 v[160:161], v[160:161], 0, v[158:159]
	global_store_dwordx4 v[208:209], v[202:205], off
	v_lshlrev_b64 v[160:161], 1, v[160:161]
	s_nop 0
	v_cvt_pk_bf16_f32 v202, v172, v178
	v_cvt_pk_bf16_f32 v203, v183, v189
	v_cvt_pk_bf16_f32 v204, v194, v199
	v_cvt_pk_bf16_f32 v205, v211, v216
	v_lshl_add_u64 v[172:173], s[14:15], 0, v[206:207]
	global_store_dwordx4 v[172:173], v[202:205], off
	s_nop 1
	v_lshl_add_u64 v[172:173], s[64:65], 0, v[160:161]
	v_lshl_add_u64 v[160:161], s[14:15], 0, v[160:161]
	v_cvt_pk_bf16_f32 v202, v171, v176
	v_cvt_pk_bf16_f32 v203, v181, v187
	v_cvt_pk_bf16_f32 v204, v192, v197
	v_cvt_pk_bf16_f32 v205, v210, v215
	global_store_dwordx4 v[172:173], v[202:205], off
	s_nop 1
	v_cvt_pk_bf16_f32 v202, v131, v175
	v_cvt_pk_bf16_f32 v203, v180, v185
	v_cvt_pk_bf16_f32 v204, v191, v196
	v_cvt_pk_bf16_f32 v205, v212, v213
	global_store_dwordx4 v[160:161], v[202:205], off
	s_and_saveexec_b64 s[0:1], s[4:5]
	s_cbranch_execz .LBB0_1147
	v_mul_f32_e32 v131, 0x3fb8aa3b, v201
	v_exp_f32_e32 v183, v131
	v_mul_f32_e32 v131, 0x3fb8aa3b, v200
	v_exp_f32_e32 v182, v131
	v_mul_f32_e32 v131, 0x3fb8aa3b, v195
	v_exp_f32_e32 v181, v131
	v_mul_f32_e32 v131, 0x3fb8aa3b, v190
	v_exp_f32_e32 v180, v131
	v_mul_f32_e32 v131, 0x3fb8aa3b, v184
	v_exp_f32_e32 v177, v131
	v_mul_f32_e32 v131, 0x3fb8aa3b, v179
	v_exp_f32_e32 v176, v131
	v_mul_f32_e32 v131, 0x3fb8aa3b, v174
	v_mul_f32_e32 v130, 0x3fb8aa3b, v130
	v_exp_f32_e32 v175, v131
	v_exp_f32_e32 v174, v130
	s_lshl_b64 s[8:9], s[38:39], 2
	s_add_u32 s8, s47, s8
	s_addc_u32 s9, s52, s9
	v_lshl_add_u64 v[130:131], v[158:159], 2, s[8:9]
	global_store_dwordx4 v[130:131], v[174:177], off
	global_store_dwordx4 v[130:131], v[180:183], off offset:16
; __device__ __forceinline__ unsigned cvt_pk_bf16(float lo, float hi) { unsigned r; asm volatile("v_cvt_pk_bf16_f32 %0, %1, %2" : "=v"(r) : "v"(lo), "v"(hi)); return r; }
; __device__ __forceinline__ float row_scan16(float v) { v += dpp_shr0<0x111>(v); v += dpp_shr0<0x112>(v); v += dpp_shr0<0x114>(v); v += dpp_shr0<0x118>(v); return v; }
; __device__ __forceinline__ float row_last16(float v, int lane) { return __builtin_bit_cast(float, __builtin_amdgcn_ds_bpermute((lane | 15) << 2, __builtin_bit_cast(int, v))); }
;     __device__ __forceinline__ void operator()(const f32x4 (&acc)[2][2][4][2], const Unit& u, int wr, int wc, int fr, int fq) const {
;     ...
;             for (int mp = 0; mp < 2; ++mp) {
;                 const int rowa = u.pm * BM + ai * HALF + wr * 64 + mp * 32 + fr;
;                 const int g = rowa >> 5;
;                 float qi[2][8], ki[2][8]; bf16_t* kot = KOT + ((size_t)g * 1024 + colh) * 32 + fr;
;                 float dec[8];
; #pragma unroll
;                 for (int n = 0; n < 2; ++n)
; #pragma unroll
;                     for (int q = 0; q < 4; ++q) { const int j = 4 * n + q;
;                         const float k0 = om[n][q] / (1.0f + __expf(acc[ai][1][2 * mp][n][q])), k1 = om[n][q] / (1.0f + __expf(acc[ai][1][2 * mp + 1][n][q]));
;                         const float p0 = row_scan16(__logf(1.0f - k0)); const float t0 = row_last16(p0, lane);
;                         const float p1 = row_scan16(__logf(1.0f - k1)) + t0; const float bl = row_last16(p1, lane);
;                         const float e0 = __expf(p0), e1 = __expf(p1);
;                         qi[0][j] = acc[ai][0][2 * mp][n][q] * e0; qi[1][j] = acc[ai][0][2 * mp + 1][n][q] * e1;
;                         ki[0][j] = k0 * __expf(-p0); ki[1][j] = k1 * __expf(-p1);
;                         kot[(size_t)j * 32] = (bf16_t)cvt_pk_bf16(k0 * __expf(bl - p0), 0.f); kot[(size_t)j * 32 + 16] = (bf16_t)cvt_pk_bf16(k1 * __expf(bl - p1), 0.f);
;                         dec[j] = __expf(bl); }
.LBB0_1147:
	s_or_b64 exec, exec, s[0:1]
	v_mul_f32_e32 v130, 0x3fb8aa3b, v82
	v_exp_f32_e32 v130, v130
	s_or_b32 s3, s2, 32
	s_ashr_i32 s0, s3, 5
	s_ashr_i32 s1, s0, 31
	v_add_f32_e32 v160, 1.0, v130
	s_lshl_b64 s[8:9], s[0:1], 10
	v_mul_f32_e32 v174, 0x3fb8aa3b, v70
	v_exp_f32_e32 v174, v174
	v_lshl_add_u64 v[130:131], s[8:9], 0, v[158:159]
	v_add_f32_e32 v172, 1.0, v174
	v_rcp_f32_e32 v161, v160
	s_nop 0
	v_mul_f32_e32 v176, v170, v161
	v_lshlrev_b64 v[130:131], 6, v[130:131]
	v_sub_f32_e32 v171, 1.0, v176
	v_log_f32_e32 v171, v171
	v_rcp_f32_e32 v160, v172
	s_nop 0
	v_mul_f32_e32 v174, v170, v160
	v_lshl_add_u64 v[130:131], v[148:149], 0, v[130:131]
	v_mul_f32_e32 v179, 0x3fb8aa3b, v71
	v_exp_f32_e32 v179, v179
	v_mul_f32_e32 v160, 0x3f317218, v171
	v_sub_f32_e32 v161, 1.0, v174
	s_nop 0
	v_add_f32_dpp v160, v160, v160 row_shr:1 row_mask:0xf bank_mask:0xf bound_ctrl:1
	v_mul_f32_e32 v184, 0x3fb8aa3b, v72
	v_log_f32_e32 v161, v161
	v_add_f32_dpp v160, v160, v160 row_shr:2 row_mask:0xf bank_mask:0xf bound_ctrl:1
	v_exp_f32_e32 v184, v184
	v_mul_f32_e32 v190, 0x3fb8aa3b, v73
	v_add_f32_dpp v160, v160, v160 row_shr:4 row_mask:0xf bank_mask:0xf bound_ctrl:1
	s_nop 1
	v_add_f32_dpp v171, v160, v160 row_shr:8 row_mask:0xf bank_mask:0xf bound_ctrl:1
	ds_bpermute_b32 v160, v162, v171
	v_mul_f32_e32 v161, 0x3f317218, v161
	v_exp_f32_e32 v190, v190
	v_mul_f32_e32 v195, 0x3fb8aa3b, v66
	v_add_f32_dpp v161, v161, v161 row_shr:1 row_mask:0xf bank_mask:0xf bound_ctrl:1
	v_exp_f32_e32 v195, v195
	s_nop 0
	v_add_f32_dpp v161, v161, v161 row_shr:2 row_mask:0xf bank_mask:0xf bound_ctrl:1
	s_nop 1
	v_add_f32_dpp v161, v161, v161 row_shr:4 row_mask:0xf bank_mask:0xf bound_ctrl:1
	s_nop 1
	v_add_f32_dpp v161, v161, v161 row_shr:8 row_mask:0xf bank_mask:0xf bound_ctrl:1
	s_waitcnt lgkmcnt(0)
	v_add_f32_e32 v175, v161, v160
	v_mul_f32_e32 v160, 0x3fb8aa3b, v171
	v_exp_f32_e32 v161, v160
	ds_bpermute_b32 v160, v162, v175
	v_mul_f32_e32 v172, 0x3fb8aa3b, v175
	v_exp_f32_e32 v173, v172
	v_mul_f32_e32 v172, v102, v161
	v_mul_f32_e32 v161, 0xbfb8aa3b, v171
	s_waitcnt lgkmcnt(0)
	v_sub_f32_e32 v171, v160, v171
	v_mul_f32_e32 v171, 0x3fb8aa3b, v171
	v_exp_f32_e32 v161, v161
	v_exp_f32_e32 v178, v171
	v_mul_f32_e32 v171, v86, v173
	v_mul_f32_e32 v177, 0xbfb8aa3b, v175
	v_mul_f32_e32 v173, v176, v161
	v_mul_f32_e32 v176, v176, v178
	v_cvt_pk_bf16_f32 v176, v176, v147
	global_store_short v[130:131], v176, off
	v_mul_f32_e32 v176, 0x3fb8aa3b, v83
	v_exp_f32_e32 v176, v176
	v_exp_f32_e32 v177, v177
	v_sub_f32_e32 v175, v160, v175
	v_mul_f32_e32 v175, 0x3fb8aa3b, v175
	v_exp_f32_e32 v175, v175
	v_add_f32_e32 v176, 1.0, v176
	v_mul_f32_e32 v161, v174, v177
	v_mul_f32_e32 v174, v174, v175
	v_cvt_pk_bf16_f32 v174, v174, v147
	global_store_short v[130:131], v174, off offset:32
	v_add_f32_e32 v177, 1.0, v179
	v_rcp_f32_e32 v174, v176
	s_nop 0
	v_mul_f32_e32 v181, v146, v174
	v_sub_f32_e32 v176, 1.0, v181
	v_log_f32_e32 v176, v176
	v_rcp_f32_e32 v174, v177
	s_nop 0
	v_mul_f32_e32 v179, v146, v174
	s_nop 1
	v_mul_f32_e32 v174, 0x3f317218, v176
	v_sub_f32_e32 v175, 1.0, v179
	s_nop 0
	v_add_f32_dpp v174, v174, v174 row_shr:1 row_mask:0xf bank_mask:0xf bound_ctrl:1
	s_nop 0
	v_log_f32_e32 v175, v175
	v_add_f32_dpp v174, v174, v174 row_shr:2 row_mask:0xf bank_mask:0xf bound_ctrl:1
	s_nop 1
	v_add_f32_dpp v174, v174, v174 row_shr:4 row_mask:0xf bank_mask:0xf bound_ctrl:1
	s_nop 1
	v_add_f32_dpp v176, v174, v174 row_shr:8 row_mask:0xf bank_mask:0xf bound_ctrl:1
	ds_bpermute_b32 v174, v162, v176
	v_mul_f32_e32 v175, 0x3f317218, v175
	s_nop 1
	v_add_f32_dpp v175, v175, v175 row_shr:1 row_mask:0xf bank_mask:0xf bound_ctrl:1
	s_nop 1
	v_add_f32_dpp v175, v175, v175 row_shr:2 row_mask:0xf bank_mask:0xf bound_ctrl:1
	s_nop 1
	v_add_f32_dpp v175, v175, v175 row_shr:4 row_mask:0xf bank_mask:0xf bound_ctrl:1
	s_nop 1
	v_add_f32_dpp v175, v175, v175 row_shr:8 row_mask:0xf bank_mask:0xf bound_ctrl:1
	s_waitcnt lgkmcnt(0)
	v_add_f32_e32 v180, v175, v174
	v_mul_f32_e32 v174, 0x3fb8aa3b, v176
	v_exp_f32_e32 v175, v174
	ds_bpermute_b32 v174, v162, v180
	v_mul_f32_e32 v177, 0x3fb8aa3b, v180
	v_exp_f32_e32 v178, v177
	v_mul_f32_e32 v177, v103, v175
	v_mul_f32_e32 v175, 0xbfb8aa3b, v176
	s_waitcnt lgkmcnt(0)
	v_sub_f32_e32 v176, v174, v176
	v_mul_f32_e32 v176, 0x3fb8aa3b, v176
	v_exp_f32_e32 v175, v175
	v_exp_f32_e32 v183, v176
	v_mul_f32_e32 v176, v87, v178
	v_mul_f32_e32 v182, 0xbfb8aa3b, v180
	v_mul_f32_e32 v178, v181, v175
	v_mul_f32_e32 v181, v181, v183
	v_cvt_pk_bf16_f32 v181, v181, v147
	global_store_short v[130:131], v181, off offset:64
	v_mul_f32_e32 v181, 0x3fb8aa3b, v84
	v_exp_f32_e32 v181, v181
	v_exp_f32_e32 v182, v182
	v_sub_f32_e32 v180, v174, v180
	v_mul_f32_e32 v180, 0x3fb8aa3b, v180
	v_exp_f32_e32 v180, v180
	v_add_f32_e32 v181, 1.0, v181
	v_mul_f32_e32 v175, v179, v182
	v_mul_f32_e32 v179, v179, v180
	v_cvt_pk_bf16_f32 v179, v179, v147
	global_store_short v[130:131], v179, off offset:96
	v_add_f32_e32 v182, 1.0, v184
	v_rcp_f32_e32 v179, v181
	s_nop 0
	v_mul_f32_e32 v187, v136, v179
	v_sub_f32_e32 v181, 1.0, v187
	v_log_f32_e32 v181, v181
	v_rcp_f32_e32 v179, v182
	s_nop 0
	v_mul_f32_e32 v184, v136, v179
	s_nop 1
	v_mul_f32_e32 v179, 0x3f317218, v181
	v_sub_f32_e32 v180, 1.0, v184
	s_nop 0
	v_add_f32_dpp v179, v179, v179 row_shr:1 row_mask:0xf bank_mask:0xf bound_ctrl:1
	s_nop 0
	v_log_f32_e32 v180, v180
	v_add_f32_dpp v179, v179, v179 row_shr:2 row_mask:0xf bank_mask:0xf bound_ctrl:1
	s_nop 1
	v_add_f32_dpp v179, v179, v179 row_shr:4 row_mask:0xf bank_mask:0xf bound_ctrl:1
	s_nop 1
	v_add_f32_dpp v181, v179, v179 row_shr:8 row_mask:0xf bank_mask:0xf bound_ctrl:1
	ds_bpermute_b32 v179, v162, v181
	v_mul_f32_e32 v180, 0x3f317218, v180
	s_nop 1
	v_add_f32_dpp v180, v180, v180 row_shr:1 row_mask:0xf bank_mask:0xf bound_ctrl:1
	s_nop 1
	v_add_f32_dpp v180, v180, v180 row_shr:2 row_mask:0xf bank_mask:0xf bound_ctrl:1
	s_nop 1
	v_add_f32_dpp v180, v180, v180 row_shr:4 row_mask:0xf bank_mask:0xf bound_ctrl:1
	s_nop 1
	v_add_f32_dpp v180, v180, v180 row_shr:8 row_mask:0xf bank_mask:0xf bound_ctrl:1
	s_waitcnt lgkmcnt(0)
; __device__ __forceinline__ unsigned cvt_pk_bf16(float lo, float hi) { unsigned r; asm volatile("v_cvt_pk_bf16_f32 %0, %1, %2" : "=v"(r) : "v"(lo), "v"(hi)); return r; }
; __device__ __forceinline__ float row_scan16(float v) { v += dpp_shr0<0x111>(v); v += dpp_shr0<0x112>(v); v += dpp_shr0<0x114>(v); v += dpp_shr0<0x118>(v); return v; }
; __device__ __forceinline__ float row_last16(float v, int lane) { return __builtin_bit_cast(float, __builtin_amdgcn_ds_bpermute((lane | 15) << 2, __builtin_bit_cast(int, v))); }
;     __device__ __forceinline__ void operator()(const f32x4 (&acc)[2][2][4][2], const Unit& u, int wr, int wc, int fr, int fq) const {
;     ...
;                 for (int n = 0; n < 2; ++n)
; #pragma unroll
;                     for (int q = 0; q < 4; ++q) { const int j = 4 * n + q;
;                         const float k0 = om[n][q] / (1.0f + __expf(acc[ai][1][2 * mp][n][q])), k1 = om[n][q] / (1.0f + __expf(acc[ai][1][2 * mp + 1][n][q]));
;                         const float p0 = row_scan16(__logf(1.0f - k0)); const float t0 = row_last16(p0, lane);
;                         const float p1 = row_scan16(__logf(1.0f - k1)) + t0; const float bl = row_last16(p1, lane);
;                         const float e0 = __expf(p0), e1 = __expf(p1);
;                         qi[0][j] = acc[ai][0][2 * mp][n][q] * e0; qi[1][j] = acc[ai][0][2 * mp + 1][n][q] * e1;
;                         ki[0][j] = k0 * __expf(-p0); ki[1][j] = k1 * __expf(-p1);
;                         kot[(size_t)j * 32] = (bf16_t)cvt_pk_bf16(k0 * __expf(bl - p0), 0.f); kot[(size_t)j * 32 + 16] = (bf16_t)cvt_pk_bf16(k1 * __expf(bl - p1), 0.f);
;                         dec[j] = __expf(bl); }
	v_add_f32_e32 v185, v180, v179
	v_mul_f32_e32 v179, 0x3fb8aa3b, v181
	v_exp_f32_e32 v180, v179
	ds_bpermute_b32 v179, v162, v185
	v_mul_f32_e32 v182, 0x3fb8aa3b, v185
	v_exp_f32_e32 v183, v182
	v_mul_f32_e32 v182, v104, v180
	v_mul_f32_e32 v180, 0xbfb8aa3b, v181
	s_waitcnt lgkmcnt(0)
	v_sub_f32_e32 v181, v179, v181
	v_mul_f32_e32 v181, 0x3fb8aa3b, v181
	v_exp_f32_e32 v180, v180
	v_exp_f32_e32 v189, v181
	v_mul_f32_e32 v181, v88, v183
	v_mul_f32_e32 v188, 0xbfb8aa3b, v185
	v_mul_f32_e32 v183, v187, v180
	v_mul_f32_e32 v187, v187, v189
	v_cvt_pk_bf16_f32 v187, v187, v147
	global_store_short v[130:131], v187, off offset:128
	v_mul_f32_e32 v187, 0x3fb8aa3b, v85
	v_exp_f32_e32 v187, v187
	v_exp_f32_e32 v188, v188
	v_sub_f32_e32 v185, v179, v185
	v_mul_f32_e32 v185, 0x3fb8aa3b, v185
	v_exp_f32_e32 v185, v185
	v_add_f32_e32 v187, 1.0, v187
	v_mul_f32_e32 v180, v184, v188
	v_mul_f32_e32 v184, v184, v185
	v_cvt_pk_bf16_f32 v184, v184, v147
	global_store_short v[130:131], v184, off offset:160
	v_add_f32_e32 v188, 1.0, v190
	v_rcp_f32_e32 v184, v187
	s_nop 0
	v_mul_f32_e32 v192, v137, v184
	v_sub_f32_e32 v187, 1.0, v192
	v_log_f32_e32 v187, v187
	v_rcp_f32_e32 v184, v188
	s_nop 0
	v_mul_f32_e32 v190, v137, v184
	s_nop 1
	v_mul_f32_e32 v184, 0x3f317218, v187
	v_sub_f32_e32 v185, 1.0, v190
	s_nop 0
	v_add_f32_dpp v184, v184, v184 row_shr:1 row_mask:0xf bank_mask:0xf bound_ctrl:1
	s_nop 0
	v_log_f32_e32 v185, v185
	v_add_f32_dpp v184, v184, v184 row_shr:2 row_mask:0xf bank_mask:0xf bound_ctrl:1
	s_nop 1
	v_add_f32_dpp v184, v184, v184 row_shr:4 row_mask:0xf bank_mask:0xf bound_ctrl:1
	s_nop 1
	v_add_f32_dpp v187, v184, v184 row_shr:8 row_mask:0xf bank_mask:0xf bound_ctrl:1
	ds_bpermute_b32 v184, v162, v187
	v_mul_f32_e32 v185, 0x3f317218, v185
	s_nop 1
	v_add_f32_dpp v185, v185, v185 row_shr:1 row_mask:0xf bank_mask:0xf bound_ctrl:1
	s_nop 1
	v_add_f32_dpp v185, v185, v185 row_shr:2 row_mask:0xf bank_mask:0xf bound_ctrl:1
	s_nop 1
	v_add_f32_dpp v185, v185, v185 row_shr:4 row_mask:0xf bank_mask:0xf bound_ctrl:1
	s_nop 1
	v_add_f32_dpp v185, v185, v185 row_shr:8 row_mask:0xf bank_mask:0xf bound_ctrl:1
	s_waitcnt lgkmcnt(0)
	v_add_f32_e32 v191, v185, v184
	v_mul_f32_e32 v184, 0x3fb8aa3b, v187
	v_exp_f32_e32 v185, v184
	ds_bpermute_b32 v184, v162, v191
	v_mul_f32_e32 v188, 0x3fb8aa3b, v191
	v_exp_f32_e32 v189, v188
	v_mul_f32_e32 v188, v105, v185
	v_mul_f32_e32 v185, 0xbfb8aa3b, v187
	s_waitcnt lgkmcnt(0)
	v_sub_f32_e32 v187, v184, v187
	v_mul_f32_e32 v187, 0x3fb8aa3b, v187
	v_exp_f32_e32 v185, v185
	v_exp_f32_e32 v194, v187
	v_mul_f32_e32 v187, v89, v189
	v_mul_f32_e32 v193, 0xbfb8aa3b, v191
	v_mul_f32_e32 v189, v192, v185
	v_mul_f32_e32 v192, v192, v194
	v_cvt_pk_bf16_f32 v192, v192, v147
	global_store_short v[130:131], v192, off offset:192
	v_mul_f32_e32 v192, 0x3fb8aa3b, v74
	v_exp_f32_e32 v192, v192
	v_exp_f32_e32 v193, v193
	v_sub_f32_e32 v191, v184, v191
	v_mul_f32_e32 v191, 0x3fb8aa3b, v191
	v_exp_f32_e32 v191, v191
	v_add_f32_e32 v192, 1.0, v192
	v_mul_f32_e32 v185, v190, v193
	v_mul_f32_e32 v190, v190, v191
	v_cvt_pk_bf16_f32 v190, v190, v147
	global_store_short v[130:131], v190, off offset:224
	v_add_f32_e32 v193, 1.0, v195
	v_rcp_f32_e32 v190, v192
	s_nop 0
	v_mul_f32_e32 v191, v135, v190
	v_sub_f32_e32 v194, 1.0, v191
	v_log_f32_e32 v194, v194
	v_rcp_f32_e32 v190, v193
	s_nop 0
	v_mul_f32_e32 v192, v135, v190
	s_nop 1
	v_mul_f32_e32 v190, 0x3f317218, v194
	v_sub_f32_e32 v193, 1.0, v192
	s_nop 0
	v_add_f32_dpp v190, v190, v190 row_shr:1 row_mask:0xf bank_mask:0xf bound_ctrl:1
	s_nop 0
	v_log_f32_e32 v193, v193
	v_add_f32_dpp v190, v190, v190 row_shr:2 row_mask:0xf bank_mask:0xf bound_ctrl:1
	s_nop 1
	v_add_f32_dpp v190, v190, v190 row_shr:4 row_mask:0xf bank_mask:0xf bound_ctrl:1
	s_nop 1
	v_add_f32_dpp v194, v190, v190 row_shr:8 row_mask:0xf bank_mask:0xf bound_ctrl:1
	ds_bpermute_b32 v190, v162, v194
	v_mul_f32_e32 v193, 0x3f317218, v193
	s_nop 1
	v_add_f32_dpp v193, v193, v193 row_shr:1 row_mask:0xf bank_mask:0xf bound_ctrl:1
	s_nop 1
	v_add_f32_dpp v193, v193, v193 row_shr:2 row_mask:0xf bank_mask:0xf bound_ctrl:1
	s_nop 1
	v_add_f32_dpp v193, v193, v193 row_shr:4 row_mask:0xf bank_mask:0xf bound_ctrl:1
	s_nop 1
	v_add_f32_dpp v193, v193, v193 row_shr:8 row_mask:0xf bank_mask:0xf bound_ctrl:1
	s_waitcnt lgkmcnt(0)
	v_add_f32_e32 v193, v193, v190
	v_mul_f32_e32 v190, 0x3fb8aa3b, v194
	v_exp_f32_e32 v195, v190
	ds_bpermute_b32 v190, v162, v193
	v_mul_f32_e32 v196, 0x3fb8aa3b, v193
	v_mul_f32_e32 v198, 0xbfb8aa3b, v193
	v_mul_f32_e32 v197, v94, v195
	v_mul_f32_e32 v195, 0xbfb8aa3b, v194
	s_waitcnt lgkmcnt(0)
	v_sub_f32_e32 v194, v190, v194
	v_mul_f32_e32 v194, 0x3fb8aa3b, v194
	v_exp_f32_e32 v195, v195
	v_exp_f32_e32 v194, v194
	v_sub_f32_e32 v193, v190, v193
	v_mul_f32_e32 v193, 0x3fb8aa3b, v193
	v_mul_f32_e32 v203, v191, v195
	v_mul_f32_e32 v191, v191, v194
	v_cvt_pk_bf16_f32 v191, v191, v147
	global_store_short v[130:131], v191, off offset:256
	v_mul_f32_e32 v191, 0x3fb8aa3b, v75
	v_exp_f32_e32 v191, v191
	v_exp_f32_e32 v198, v198
	v_exp_f32_e32 v193, v193
	v_exp_f32_e32 v196, v196
	v_add_f32_e32 v191, 1.0, v191
	v_mul_f32_e32 v204, v192, v198
	v_mul_f32_e32 v192, v192, v193
	v_cvt_pk_bf16_f32 v192, v192, v147
	v_mul_f32_e32 v202, v78, v196
	global_store_short v[130:131], v192, off offset:288
	v_mul_f32_e32 v196, 0x3fb8aa3b, v67
	v_exp_f32_e32 v196, v196
	s_nop 0
	v_add_f32_e32 v194, 1.0, v196
	v_rcp_f32_e32 v192, v191
	s_nop 0
	v_mul_f32_e32 v192, v134, v192
	v_sub_f32_e32 v195, 1.0, v192
	v_log_f32_e32 v195, v195
	v_rcp_f32_e32 v191, v194
	s_nop 0
	v_mul_f32_e32 v193, v134, v191
	s_nop 1
	v_mul_f32_e32 v191, 0x3f317218, v195
	v_sub_f32_e32 v194, 1.0, v193
	s_nop 0
	v_add_f32_dpp v191, v191, v191 row_shr:1 row_mask:0xf bank_mask:0xf bound_ctrl:1
	s_nop 0
	v_log_f32_e32 v194, v194
	v_add_f32_dpp v191, v191, v191 row_shr:2 row_mask:0xf bank_mask:0xf bound_ctrl:1
	s_nop 1
	v_add_f32_dpp v191, v191, v191 row_shr:4 row_mask:0xf bank_mask:0xf bound_ctrl:1
	s_nop 1
	v_add_f32_dpp v195, v191, v191 row_shr:8 row_mask:0xf bank_mask:0xf bound_ctrl:1
	ds_bpermute_b32 v191, v162, v195
	v_mul_f32_e32 v194, 0x3f317218, v194
	v_mul_f32_e32 v199, 0xbfb8aa3b, v195
	v_exp_f32_e32 v199, v199
	v_add_f32_dpp v194, v194, v194 row_shr:1 row_mask:0xf bank_mask:0xf bound_ctrl:1
	v_mul_f32_e32 v206, v192, v199
	s_nop 0
	v_add_f32_dpp v194, v194, v194 row_shr:2 row_mask:0xf bank_mask:0xf bound_ctrl:1
	v_mul_f32_e32 v199, 0x3fb8aa3b, v68
	v_exp_f32_e32 v199, v199
	v_add_f32_dpp v194, v194, v194 row_shr:4 row_mask:0xf bank_mask:0xf bound_ctrl:1
	s_nop 1
	v_add_f32_dpp v194, v194, v194 row_shr:8 row_mask:0xf bank_mask:0xf bound_ctrl:1
	s_waitcnt lgkmcnt(0)
; __device__ __forceinline__ unsigned cvt_pk_bf16(float lo, float hi) { unsigned r; asm volatile("v_cvt_pk_bf16_f32 %0, %1, %2" : "=v"(r) : "v"(lo), "v"(hi)); return r; }
; __device__ __forceinline__ float row_scan16(float v) { v += dpp_shr0<0x111>(v); v += dpp_shr0<0x112>(v); v += dpp_shr0<0x114>(v); v += dpp_shr0<0x118>(v); return v; }
;     __device__ __forceinline__ void operator()(const f32x4 (&acc)[2][2][4][2], const Unit& u, int wr, int wc, int fr, int fq) const {
;     ...
;                 for (int n = 0; n < 2; ++n)
; #pragma unroll
;                     for (int q = 0; q < 4; ++q) { const int j = 4 * n + q;
;                         const float k0 = om[n][q] / (1.0f + __expf(acc[ai][1][2 * mp][n][q])), k1 = om[n][q] / (1.0f + __expf(acc[ai][1][2 * mp + 1][n][q]));
;                         const float p0 = row_scan16(__logf(1.0f - k0)); const float t0 = row_last16(p0, lane);
;                         const float p1 = row_scan16(__logf(1.0f - k1)) + t0; const float bl = row_last16(p1, lane);
;                         const float e0 = __expf(p0), e1 = __expf(p1);
;                         qi[0][j] = acc[ai][0][2 * mp][n][q] * e0; qi[1][j] = acc[ai][0][2 * mp + 1][n][q] * e1;
;                         ki[0][j] = k0 * __expf(-p0); ki[1][j] = k1 * __expf(-p1);
;                         kot[(size_t)j * 32] = (bf16_t)cvt_pk_bf16(k0 * __expf(bl - p0), 0.f); kot[(size_t)j * 32 + 16] = (bf16_t)cvt_pk_bf16(k1 * __expf(bl - p1), 0.f);
;                         dec[j] = __expf(bl); }
; #pragma unroll
;                 for (int mm = 0; mm < 2; ++mm) { const size_t ro = (size_t)(rowa + 16 * mm) * 1024 + colh;
;                     u32x4 w; w.x = cvt_pk_bf16(qi[mm][0], qi[mm][1]); w.y = cvt_pk_bf16(qi[mm][2], qi[mm][3]); w.z = cvt_pk_bf16(qi[mm][4], qi[mm][5]); w.w = cvt_pk_bf16(qi[mm][6], qi[mm][7]);
;                     *(u32x4*)(CQ + ro) = w;
;                     w.x = cvt_pk_bf16(ki[mm][0], ki[mm][1]); w.y = cvt_pk_bf16(ki[mm][2], ki[mm][3]); w.z = cvt_pk_bf16(ki[mm][4], ki[mm][5]); w.w = cvt_pk_bf16(ki[mm][6], ki[mm][7]);
;                     *(u32x4*)(CK + ro) = w; }
;                 if (fr == 15) { float* dp = DEC + (size_t)g * 1024 + colh; *(f32x4*)dp = (f32x4){dec[0], dec[1], dec[2], dec[3]}; *(f32x4*)(dp + 4) = (f32x4){dec[4], dec[5], dec[6], dec[7]}; }
	v_add_f32_e32 v194, v194, v191
	v_mul_f32_e32 v191, 0x3fb8aa3b, v195
	v_exp_f32_e32 v196, v191
	ds_bpermute_b32 v191, v162, v194
	v_mul_f32_e32 v198, 0x3fb8aa3b, v194
	v_exp_f32_e32 v198, v198
	v_mul_f32_e32 v200, 0xbfb8aa3b, v194
	v_exp_f32_e32 v200, v200
	s_waitcnt lgkmcnt(0)
	v_sub_f32_e32 v195, v191, v195
	v_mul_f32_e32 v195, 0x3fb8aa3b, v195
	v_exp_f32_e32 v195, v195
	v_sub_f32_e32 v194, v191, v194
	v_mul_f32_e32 v194, 0x3fb8aa3b, v194
	v_exp_f32_e32 v194, v194
	v_mul_f32_e32 v192, v192, v195
	v_cvt_pk_bf16_f32 v192, v192, v147
	global_store_short v[130:131], v192, off offset:320
	v_mul_f32_e32 v192, 0x3fb8aa3b, v76
	v_exp_f32_e32 v192, v192
	v_mul_f32_e32 v205, v79, v198
	v_mul_f32_e32 v207, v193, v200
	v_mul_f32_e32 v193, v193, v194
	v_add_f32_e32 v192, 1.0, v192
	v_cvt_pk_bf16_f32 v193, v193, v147
	global_store_short v[130:131], v193, off offset:352
	v_mul_f32_e32 v196, v95, v196
	v_add_f32_e32 v195, 1.0, v199
	v_rcp_f32_e32 v193, v192
	s_nop 0
	v_mul_f32_e32 v193, v132, v193
	v_sub_f32_e32 v198, 1.0, v193
	v_log_f32_e32 v198, v198
	v_rcp_f32_e32 v192, v195
	s_nop 0
	v_mul_f32_e32 v194, v132, v192
	s_nop 1
	v_mul_f32_e32 v192, 0x3f317218, v198
	v_sub_f32_e32 v195, 1.0, v194
	s_nop 0
	v_add_f32_dpp v192, v192, v192 row_shr:1 row_mask:0xf bank_mask:0xf bound_ctrl:1
	s_nop 0
	v_log_f32_e32 v195, v195
	v_add_f32_dpp v192, v192, v192 row_shr:2 row_mask:0xf bank_mask:0xf bound_ctrl:1
	s_nop 1
	v_add_f32_dpp v192, v192, v192 row_shr:4 row_mask:0xf bank_mask:0xf bound_ctrl:1
	s_nop 1
	v_add_f32_dpp v198, v192, v192 row_shr:8 row_mask:0xf bank_mask:0xf bound_ctrl:1
	ds_bpermute_b32 v192, v162, v198
	v_mul_f32_e32 v195, 0x3f317218, v195
	s_nop 1
	v_add_f32_dpp v195, v195, v195 row_shr:1 row_mask:0xf bank_mask:0xf bound_ctrl:1
	s_nop 1
	v_add_f32_dpp v195, v195, v195 row_shr:2 row_mask:0xf bank_mask:0xf bound_ctrl:1
	s_nop 1
	v_add_f32_dpp v195, v195, v195 row_shr:4 row_mask:0xf bank_mask:0xf bound_ctrl:1
	s_nop 1
	v_add_f32_dpp v195, v195, v195 row_shr:8 row_mask:0xf bank_mask:0xf bound_ctrl:1
	s_waitcnt lgkmcnt(0)
	v_add_f32_e32 v195, v195, v192
	v_mul_f32_e32 v192, 0x3fb8aa3b, v198
	v_exp_f32_e32 v199, v192
	ds_bpermute_b32 v192, v162, v195
	v_mul_f32_e32 v200, 0x3fb8aa3b, v195
	v_mul_f32_e32 v208, 0xbfb8aa3b, v195
	v_mul_f32_e32 v201, v96, v199
	v_mul_f32_e32 v199, 0xbfb8aa3b, v198
	s_waitcnt lgkmcnt(0)
	v_sub_f32_e32 v198, v192, v198
	v_mul_f32_e32 v198, 0x3fb8aa3b, v198
	v_exp_f32_e32 v199, v199
	v_exp_f32_e32 v198, v198
	v_sub_f32_e32 v195, v192, v195
	v_mul_f32_e32 v195, 0x3fb8aa3b, v195
	v_mul_f32_e32 v210, v193, v199
	v_mul_f32_e32 v193, v193, v198
	v_cvt_pk_bf16_f32 v193, v193, v147
	global_store_short v[130:131], v193, off offset:384
	v_mul_f32_e32 v193, 0x3fb8aa3b, v77
	v_exp_f32_e32 v193, v193
	v_exp_f32_e32 v208, v208
	v_exp_f32_e32 v195, v195
	v_exp_f32_e32 v200, v200
	v_add_f32_e32 v193, 1.0, v193
	v_mul_f32_e32 v208, v194, v208
	v_mul_f32_e32 v194, v194, v195
	v_cvt_pk_bf16_f32 v194, v194, v147
	v_mul_f32_e32 v209, v80, v200
	global_store_short v[130:131], v194, off offset:416
	v_mul_f32_e32 v200, 0x3fb8aa3b, v69
	v_exp_f32_e32 v200, v200
	s_nop 0
	v_add_f32_e32 v198, 1.0, v200
	v_rcp_f32_e32 v194, v193
	s_nop 0
	v_mul_f32_e32 v194, v133, v194
	v_sub_f32_e32 v199, 1.0, v194
	v_log_f32_e32 v199, v199
	v_rcp_f32_e32 v193, v198
	s_nop 0
	v_mul_f32_e32 v195, v133, v193
	s_nop 1
	v_mul_f32_e32 v193, 0x3f317218, v199
	v_sub_f32_e32 v198, 1.0, v195
	s_nop 0
	v_add_f32_dpp v193, v193, v193 row_shr:1 row_mask:0xf bank_mask:0xf bound_ctrl:1
	s_nop 0
	v_log_f32_e32 v198, v198
	v_add_f32_dpp v193, v193, v193 row_shr:2 row_mask:0xf bank_mask:0xf bound_ctrl:1
	s_nop 1
	v_add_f32_dpp v193, v193, v193 row_shr:4 row_mask:0xf bank_mask:0xf bound_ctrl:1
	s_nop 1
	v_add_f32_dpp v199, v193, v193 row_shr:8 row_mask:0xf bank_mask:0xf bound_ctrl:1
	ds_bpermute_b32 v193, v162, v199
	v_mul_f32_e32 v198, 0x3f317218, v198
	v_mul_f32_e32 v200, 0x3fb8aa3b, v199
	v_mul_f32_e32 v212, 0xbfb8aa3b, v199
	v_add_f32_dpp v198, v198, v198 row_shr:1 row_mask:0xf bank_mask:0xf bound_ctrl:1
	v_exp_f32_e32 v212, v212
	v_exp_f32_e32 v200, v200
	v_add_f32_dpp v198, v198, v198 row_shr:2 row_mask:0xf bank_mask:0xf bound_ctrl:1
	v_mul_f32_e32 v212, v194, v212
	s_nop 0
	v_add_f32_dpp v198, v198, v198 row_shr:4 row_mask:0xf bank_mask:0xf bound_ctrl:1
	v_mul_f32_e32 v200, v97, v200
	s_nop 0
	v_add_f32_dpp v198, v198, v198 row_shr:8 row_mask:0xf bank_mask:0xf bound_ctrl:1
	s_waitcnt lgkmcnt(0)
	v_add_f32_e32 v198, v198, v193
	ds_bpermute_b32 v193, v162, v198
	v_mul_f32_e32 v211, 0x3fb8aa3b, v198
	v_mul_f32_e32 v213, 0xbfb8aa3b, v198
	v_exp_f32_e32 v213, v213
	v_exp_f32_e32 v211, v211
	s_waitcnt lgkmcnt(0)
	v_sub_f32_e32 v199, v193, v199
	v_mul_f32_e32 v199, 0x3fb8aa3b, v199
	v_exp_f32_e32 v199, v199
	v_sub_f32_e32 v198, v193, v198
	v_mul_f32_e32 v198, 0x3fb8aa3b, v198
	v_exp_f32_e32 v198, v198
	v_mul_f32_e32 v194, v194, v199
	v_cvt_pk_bf16_f32 v194, v194, v147
	global_store_short v[130:131], v194, off offset:448
	v_mul_f32_e32 v194, v195, v198
	v_cvt_pk_bf16_f32 v194, v194, v147
	global_store_short v[130:131], v194, off offset:480
	v_or_b32_e32 v130, s3, v1
	v_ashrrev_i32_e32 v131, 31, v130
	v_mul_f32_e32 v213, v195, v213
	v_lshlrev_b64 v[194:195], 10, v[130:131]
	v_or_b32_e32 v130, 16, v130
	v_lshl_add_u64 v[198:199], v[194:195], 0, v[158:159]
	v_ashrrev_i32_e32 v131, 31, v130
	v_lshlrev_b64 v[198:199], 1, v[198:199]
	v_lshlrev_b64 v[130:131], 10, v[130:131]
	v_cvt_pk_bf16_f32 v194, v172, v177
	v_cvt_pk_bf16_f32 v195, v182, v188
	v_cvt_pk_bf16_f32 v196, v197, v196
	v_cvt_pk_bf16_f32 v197, v201, v200
	v_lshl_add_u64 v[200:201], s[64:65], 0, v[198:199]
	v_lshl_add_u64 v[130:131], v[130:131], 0, v[158:159]
	global_store_dwordx4 v[200:201], v[194:197], off
	v_lshlrev_b64 v[130:131], 1, v[130:131]
	v_mul_f32_e32 v211, v81, v211
	v_cvt_pk_bf16_f32 v194, v173, v178
	v_cvt_pk_bf16_f32 v195, v183, v189
	v_cvt_pk_bf16_f32 v196, v203, v206
	v_cvt_pk_bf16_f32 v197, v210, v212
	v_lshl_add_u64 v[172:173], s[14:15], 0, v[198:199]
	global_store_dwordx4 v[172:173], v[194:197], off
	s_nop 1
	v_lshl_add_u64 v[172:173], s[64:65], 0, v[130:131]
	v_lshl_add_u64 v[130:131], s[14:15], 0, v[130:131]
	v_cvt_pk_bf16_f32 v194, v171, v176
	v_cvt_pk_bf16_f32 v195, v181, v187
	v_cvt_pk_bf16_f32 v196, v202, v205
	v_cvt_pk_bf16_f32 v197, v209, v211
	global_store_dwordx4 v[172:173], v[194:197], off
	s_nop 1
	v_cvt_pk_bf16_f32 v194, v161, v175
	v_cvt_pk_bf16_f32 v195, v180, v185
	v_cvt_pk_bf16_f32 v196, v204, v207
	v_cvt_pk_bf16_f32 v197, v208, v213
	global_store_dwordx4 v[130:131], v[194:197], off
	s_and_saveexec_b64 s[0:1], s[4:5]
	s_cbranch_execz .LBB0_1149
	v_mul_f32_e32 v130, 0x3fb8aa3b, v193
	v_exp_f32_e32 v183, v130
	v_mul_f32_e32 v130, 0x3fb8aa3b, v192
	v_exp_f32_e32 v182, v130
	v_mul_f32_e32 v130, 0x3fb8aa3b, v191
	v_exp_f32_e32 v181, v130
	v_mul_f32_e32 v130, 0x3fb8aa3b, v190
	v_exp_f32_e32 v180, v130
	v_mul_f32_e32 v130, 0x3fb8aa3b, v184
	v_exp_f32_e32 v177, v130
	v_mul_f32_e32 v130, 0x3fb8aa3b, v179
	v_exp_f32_e32 v176, v130
	v_mul_f32_e32 v130, 0x3fb8aa3b, v174
	v_exp_f32_e32 v175, v130
	v_mul_f32_e32 v130, 0x3fb8aa3b, v160
	v_exp_f32_e32 v174, v130
	s_lshl_b64 s[8:9], s[8:9], 2
	s_add_u32 s8, s47, s8
	s_addc_u32 s9, s52, s9
	v_lshl_add_u64 v[130:131], v[158:159], 2, s[8:9]
	global_store_dwordx4 v[130:131], v[174:177], off
	global_store_dwordx4 v[130:131], v[180:183], off offset:16
.LBB0_1149:
	s_or_b64 exec, exec, s[0:1]
	v_mul_f32_e32 v130, 0x3fb8aa3b, v50
	v_exp_f32_e32 v130, v130
	s_add_i32 s3, s2, 0x80
	s_ashr_i32 s0, s3, 5
	s_ashr_i32 s1, s0, 31
	v_add_f32_e32 v160, 1.0, v130
	s_lshl_b64 s[8:9], s[0:1], 10
	v_mul_f32_e32 v174, 0x3fb8aa3b, v34
	v_exp_f32_e32 v174, v174
	v_lshl_add_u64 v[130:131], s[8:9], 0, v[158:159]
	v_add_f32_e32 v172, 1.0, v174
	v_rcp_f32_e32 v161, v160
	s_nop 0
	v_mul_f32_e32 v176, v170, v161
	v_lshlrev_b64 v[130:131], 6, v[130:131]
	v_sub_f32_e32 v171, 1.0, v176
	v_log_f32_e32 v171, v171
	v_rcp_f32_e32 v160, v172
	s_nop 0
	v_mul_f32_e32 v174, v170, v160
	v_lshl_add_u64 v[130:131], v[148:149], 0, v[130:131]
	v_mul_f32_e32 v179, 0x3fb8aa3b, v35
	v_exp_f32_e32 v179, v179
	v_mul_f32_e32 v160, 0x3f317218, v171
	v_sub_f32_e32 v161, 1.0, v174
	s_nop 0
	v_add_f32_dpp v160, v160, v160 row_shr:1 row_mask:0xf bank_mask:0xf bound_ctrl:1
	v_mul_f32_e32 v184, 0x3fb8aa3b, v36
	v_log_f32_e32 v161, v161
	v_add_f32_dpp v160, v160, v160 row_shr:2 row_mask:0xf bank_mask:0xf bound_ctrl:1
	v_exp_f32_e32 v184, v184
	v_mul_f32_e32 v190, 0x3fb8aa3b, v37
	v_add_f32_dpp v160, v160, v160 row_shr:4 row_mask:0xf bank_mask:0xf bound_ctrl:1
	s_nop 1
	v_add_f32_dpp v171, v160, v160 row_shr:8 row_mask:0xf bank_mask:0xf bound_ctrl:1
	ds_bpermute_b32 v160, v162, v171
	v_mul_f32_e32 v161, 0x3f317218, v161
	v_exp_f32_e32 v190, v190
	v_mul_f32_e32 v195, 0x3fb8aa3b, v26
	v_add_f32_dpp v161, v161, v161 row_shr:1 row_mask:0xf bank_mask:0xf bound_ctrl:1
	v_exp_f32_e32 v195, v195
	s_nop 0
	v_add_f32_dpp v161, v161, v161 row_shr:2 row_mask:0xf bank_mask:0xf bound_ctrl:1
	s_nop 1
	v_add_f32_dpp v161, v161, v161 row_shr:4 row_mask:0xf bank_mask:0xf bound_ctrl:1
	s_nop 1
	v_add_f32_dpp v161, v161, v161 row_shr:8 row_mask:0xf bank_mask:0xf bound_ctrl:1
	s_waitcnt lgkmcnt(0)
	v_add_f32_e32 v175, v161, v160
	v_mul_f32_e32 v160, 0x3fb8aa3b, v171
	v_exp_f32_e32 v161, v160
	ds_bpermute_b32 v160, v162, v175
	v_mul_f32_e32 v172, 0x3fb8aa3b, v175
	v_exp_f32_e32 v173, v172
	v_mul_f32_e32 v172, v62, v161
	v_mul_f32_e32 v161, 0xbfb8aa3b, v171
	s_waitcnt lgkmcnt(0)
	v_sub_f32_e32 v171, v160, v171
	v_mul_f32_e32 v171, 0x3fb8aa3b, v171
	v_exp_f32_e32 v161, v161
	v_exp_f32_e32 v178, v171
	v_mul_f32_e32 v171, v54, v173
	v_mul_f32_e32 v177, 0xbfb8aa3b, v175
	v_mul_f32_e32 v173, v176, v161
	v_mul_f32_e32 v176, v176, v178
	v_cvt_pk_bf16_f32 v176, v176, v147
	global_store_short v[130:131], v176, off
	v_mul_f32_e32 v176, 0x3fb8aa3b, v51
	v_exp_f32_e32 v176, v176
	v_exp_f32_e32 v177, v177
	v_sub_f32_e32 v175, v160, v175
	v_mul_f32_e32 v175, 0x3fb8aa3b, v175
	v_exp_f32_e32 v175, v175
	v_add_f32_e32 v176, 1.0, v176
	v_mul_f32_e32 v161, v174, v177
	v_mul_f32_e32 v174, v174, v175
	v_cvt_pk_bf16_f32 v174, v174, v147
	global_store_short v[130:131], v174, off offset:32
	v_add_f32_e32 v177, 1.0, v179
	v_rcp_f32_e32 v174, v176
	s_nop 0
	v_mul_f32_e32 v181, v146, v174
	v_sub_f32_e32 v176, 1.0, v181
	v_log_f32_e32 v176, v176
	v_rcp_f32_e32 v174, v177
	s_nop 0
	v_mul_f32_e32 v179, v146, v174
	s_nop 1
	v_mul_f32_e32 v174, 0x3f317218, v176
	v_sub_f32_e32 v175, 1.0, v179
	s_nop 0
	v_add_f32_dpp v174, v174, v174 row_shr:1 row_mask:0xf bank_mask:0xf bound_ctrl:1
	s_nop 0
	v_log_f32_e32 v175, v175
	v_add_f32_dpp v174, v174, v174 row_shr:2 row_mask:0xf bank_mask:0xf bound_ctrl:1
	s_nop 1
	v_add_f32_dpp v174, v174, v174 row_shr:4 row_mask:0xf bank_mask:0xf bound_ctrl:1
	s_nop 1
	v_add_f32_dpp v176, v174, v174 row_shr:8 row_mask:0xf bank_mask:0xf bound_ctrl:1
	ds_bpermute_b32 v174, v162, v176
	v_mul_f32_e32 v175, 0x3f317218, v175
	s_nop 1
	v_add_f32_dpp v175, v175, v175 row_shr:1 row_mask:0xf bank_mask:0xf bound_ctrl:1
	s_nop 1
	v_add_f32_dpp v175, v175, v175 row_shr:2 row_mask:0xf bank_mask:0xf bound_ctrl:1
	s_nop 1
	v_add_f32_dpp v175, v175, v175 row_shr:4 row_mask:0xf bank_mask:0xf bound_ctrl:1
	s_nop 1
	v_add_f32_dpp v175, v175, v175 row_shr:8 row_mask:0xf bank_mask:0xf bound_ctrl:1
	s_waitcnt lgkmcnt(0)
	v_add_f32_e32 v180, v175, v174
	v_mul_f32_e32 v174, 0x3fb8aa3b, v176
	v_exp_f32_e32 v175, v174
	ds_bpermute_b32 v174, v162, v180
	v_mul_f32_e32 v177, 0x3fb8aa3b, v180
	v_exp_f32_e32 v178, v177
	v_mul_f32_e32 v177, v63, v175
	v_mul_f32_e32 v175, 0xbfb8aa3b, v176
	s_waitcnt lgkmcnt(0)
; __device__ __forceinline__ unsigned cvt_pk_bf16(float lo, float hi) { unsigned r; asm volatile("v_cvt_pk_bf16_f32 %0, %1, %2" : "=v"(r) : "v"(lo), "v"(hi)); return r; }
; __device__ __forceinline__ float row_scan16(float v) { v += dpp_shr0<0x111>(v); v += dpp_shr0<0x112>(v); v += dpp_shr0<0x114>(v); v += dpp_shr0<0x118>(v); return v; }
; __device__ __forceinline__ float row_last16(float v, int lane) { return __builtin_bit_cast(float, __builtin_amdgcn_ds_bpermute((lane | 15) << 2, __builtin_bit_cast(int, v))); }
;     __device__ __forceinline__ void operator()(const f32x4 (&acc)[2][2][4][2], const Unit& u, int wr, int wc, int fr, int fq) const {
;     ...
;                 for (int n = 0; n < 2; ++n)
; #pragma unroll
;                     for (int q = 0; q < 4; ++q) { const int j = 4 * n + q;
;                         const float k0 = om[n][q] / (1.0f + __expf(acc[ai][1][2 * mp][n][q])), k1 = om[n][q] / (1.0f + __expf(acc[ai][1][2 * mp + 1][n][q]));
;                         const float p0 = row_scan16(__logf(1.0f - k0)); const float t0 = row_last16(p0, lane);
;                         const float p1 = row_scan16(__logf(1.0f - k1)) + t0; const float bl = row_last16(p1, lane);
;                         const float e0 = __expf(p0), e1 = __expf(p1);
;                         qi[0][j] = acc[ai][0][2 * mp][n][q] * e0; qi[1][j] = acc[ai][0][2 * mp + 1][n][q] * e1;
;                         ki[0][j] = k0 * __expf(-p0); ki[1][j] = k1 * __expf(-p1);
;                         kot[(size_t)j * 32] = (bf16_t)cvt_pk_bf16(k0 * __expf(bl - p0), 0.f); kot[(size_t)j * 32 + 16] = (bf16_t)cvt_pk_bf16(k1 * __expf(bl - p1), 0.f);
;                         dec[j] = __expf(bl); }
	v_sub_f32_e32 v176, v174, v176
	v_mul_f32_e32 v176, 0x3fb8aa3b, v176
	v_exp_f32_e32 v175, v175
	v_exp_f32_e32 v183, v176
	v_mul_f32_e32 v176, v55, v178
	v_mul_f32_e32 v182, 0xbfb8aa3b, v180
	v_mul_f32_e32 v178, v181, v175
	v_mul_f32_e32 v181, v181, v183
	v_cvt_pk_bf16_f32 v181, v181, v147
	global_store_short v[130:131], v181, off offset:64
	v_mul_f32_e32 v181, 0x3fb8aa3b, v52
	v_exp_f32_e32 v181, v181
	v_exp_f32_e32 v182, v182
	v_sub_f32_e32 v180, v174, v180
	v_mul_f32_e32 v180, 0x3fb8aa3b, v180
	v_exp_f32_e32 v180, v180
	v_add_f32_e32 v181, 1.0, v181
	v_mul_f32_e32 v175, v179, v182
	v_mul_f32_e32 v179, v179, v180
	v_cvt_pk_bf16_f32 v179, v179, v147
	global_store_short v[130:131], v179, off offset:96
	v_add_f32_e32 v182, 1.0, v184
	v_rcp_f32_e32 v179, v181
	s_nop 0
	v_mul_f32_e32 v187, v136, v179
	v_sub_f32_e32 v181, 1.0, v187
	v_log_f32_e32 v181, v181
	v_rcp_f32_e32 v179, v182
	s_nop 0
	v_mul_f32_e32 v184, v136, v179
	s_nop 1
	v_mul_f32_e32 v179, 0x3f317218, v181
	v_sub_f32_e32 v180, 1.0, v184
	s_nop 0
	v_add_f32_dpp v179, v179, v179 row_shr:1 row_mask:0xf bank_mask:0xf bound_ctrl:1
	s_nop 0
	v_log_f32_e32 v180, v180
	v_add_f32_dpp v179, v179, v179 row_shr:2 row_mask:0xf bank_mask:0xf bound_ctrl:1
	s_nop 1
	v_add_f32_dpp v179, v179, v179 row_shr:4 row_mask:0xf bank_mask:0xf bound_ctrl:1
	s_nop 1
	v_add_f32_dpp v181, v179, v179 row_shr:8 row_mask:0xf bank_mask:0xf bound_ctrl:1
	ds_bpermute_b32 v179, v162, v181
	v_mul_f32_e32 v180, 0x3f317218, v180
	s_nop 1
	v_add_f32_dpp v180, v180, v180 row_shr:1 row_mask:0xf bank_mask:0xf bound_ctrl:1
	s_nop 1
	v_add_f32_dpp v180, v180, v180 row_shr:2 row_mask:0xf bank_mask:0xf bound_ctrl:1
	s_nop 1
	v_add_f32_dpp v180, v180, v180 row_shr:4 row_mask:0xf bank_mask:0xf bound_ctrl:1
	s_nop 1
	v_add_f32_dpp v180, v180, v180 row_shr:8 row_mask:0xf bank_mask:0xf bound_ctrl:1
	s_waitcnt lgkmcnt(0)
	v_add_f32_e32 v185, v180, v179
	v_mul_f32_e32 v179, 0x3fb8aa3b, v181
	v_exp_f32_e32 v180, v179
	ds_bpermute_b32 v179, v162, v185
	v_mul_f32_e32 v182, 0x3fb8aa3b, v185
	v_exp_f32_e32 v183, v182
	v_mul_f32_e32 v182, v64, v180
	v_mul_f32_e32 v180, 0xbfb8aa3b, v181
	s_waitcnt lgkmcnt(0)
	v_sub_f32_e32 v181, v179, v181
	v_mul_f32_e32 v181, 0x3fb8aa3b, v181
	v_exp_f32_e32 v180, v180
	v_exp_f32_e32 v189, v181
	v_mul_f32_e32 v181, v56, v183
	v_mul_f32_e32 v188, 0xbfb8aa3b, v185
	v_mul_f32_e32 v183, v187, v180
	v_mul_f32_e32 v187, v187, v189
	v_cvt_pk_bf16_f32 v187, v187, v147
	global_store_short v[130:131], v187, off offset:128
	v_mul_f32_e32 v187, 0x3fb8aa3b, v53
	v_exp_f32_e32 v187, v187
	v_exp_f32_e32 v188, v188
	v_sub_f32_e32 v185, v179, v185
	v_mul_f32_e32 v185, 0x3fb8aa3b, v185
	v_exp_f32_e32 v185, v185
	v_add_f32_e32 v187, 1.0, v187
	v_mul_f32_e32 v180, v184, v188
	v_mul_f32_e32 v184, v184, v185
	v_cvt_pk_bf16_f32 v184, v184, v147
	global_store_short v[130:131], v184, off offset:160
	v_add_f32_e32 v188, 1.0, v190
	v_rcp_f32_e32 v184, v187
	s_nop 0
	v_mul_f32_e32 v192, v137, v184
	v_sub_f32_e32 v187, 1.0, v192
	v_log_f32_e32 v187, v187
	v_rcp_f32_e32 v184, v188
	s_nop 0
	v_mul_f32_e32 v190, v137, v184
	s_nop 1
	v_mul_f32_e32 v184, 0x3f317218, v187
	v_sub_f32_e32 v185, 1.0, v190
	s_nop 0
	v_add_f32_dpp v184, v184, v184 row_shr:1 row_mask:0xf bank_mask:0xf bound_ctrl:1
	s_nop 0
	v_log_f32_e32 v185, v185
	v_add_f32_dpp v184, v184, v184 row_shr:2 row_mask:0xf bank_mask:0xf bound_ctrl:1
	s_nop 1
	v_add_f32_dpp v184, v184, v184 row_shr:4 row_mask:0xf bank_mask:0xf bound_ctrl:1
	s_nop 1
	v_add_f32_dpp v187, v184, v184 row_shr:8 row_mask:0xf bank_mask:0xf bound_ctrl:1
	ds_bpermute_b32 v184, v162, v187
	v_mul_f32_e32 v185, 0x3f317218, v185
	s_nop 1
	v_add_f32_dpp v185, v185, v185 row_shr:1 row_mask:0xf bank_mask:0xf bound_ctrl:1
	s_nop 1
	v_add_f32_dpp v185, v185, v185 row_shr:2 row_mask:0xf bank_mask:0xf bound_ctrl:1
	s_nop 1
	v_add_f32_dpp v185, v185, v185 row_shr:4 row_mask:0xf bank_mask:0xf bound_ctrl:1
	s_nop 1
	v_add_f32_dpp v185, v185, v185 row_shr:8 row_mask:0xf bank_mask:0xf bound_ctrl:1
	s_waitcnt lgkmcnt(0)
	v_add_f32_e32 v191, v185, v184
	v_mul_f32_e32 v184, 0x3fb8aa3b, v187
	v_exp_f32_e32 v185, v184
	ds_bpermute_b32 v184, v162, v191
	v_mul_f32_e32 v188, 0x3fb8aa3b, v191
	v_exp_f32_e32 v189, v188
	v_mul_f32_e32 v188, v65, v185
	v_mul_f32_e32 v185, 0xbfb8aa3b, v187
	s_waitcnt lgkmcnt(0)
	v_sub_f32_e32 v187, v184, v187
	v_mul_f32_e32 v187, 0x3fb8aa3b, v187
	v_exp_f32_e32 v185, v185
	v_exp_f32_e32 v194, v187
	v_mul_f32_e32 v187, v57, v189
	v_mul_f32_e32 v193, 0xbfb8aa3b, v191
	v_mul_f32_e32 v189, v192, v185
	v_mul_f32_e32 v192, v192, v194
	v_cvt_pk_bf16_f32 v192, v192, v147
	global_store_short v[130:131], v192, off offset:192
	v_mul_f32_e32 v192, 0x3fb8aa3b, v42
	v_exp_f32_e32 v192, v192
	v_exp_f32_e32 v193, v193
	v_sub_f32_e32 v191, v184, v191
	v_mul_f32_e32 v191, 0x3fb8aa3b, v191
	v_exp_f32_e32 v191, v191
	v_add_f32_e32 v192, 1.0, v192
	v_mul_f32_e32 v185, v190, v193
	v_mul_f32_e32 v190, v190, v191
	v_cvt_pk_bf16_f32 v190, v190, v147
	global_store_short v[130:131], v190, off offset:224
	v_add_f32_e32 v193, 1.0, v195
	v_rcp_f32_e32 v190, v192
	s_nop 0
	v_mul_f32_e32 v191, v135, v190
	v_sub_f32_e32 v194, 1.0, v191
	v_log_f32_e32 v194, v194
	v_rcp_f32_e32 v190, v193
	s_nop 0
	v_mul_f32_e32 v192, v135, v190
	s_nop 1
	v_mul_f32_e32 v190, 0x3f317218, v194
	v_sub_f32_e32 v193, 1.0, v192
	s_nop 0
	v_add_f32_dpp v190, v190, v190 row_shr:1 row_mask:0xf bank_mask:0xf bound_ctrl:1
	s_nop 0
	v_log_f32_e32 v193, v193
	v_add_f32_dpp v190, v190, v190 row_shr:2 row_mask:0xf bank_mask:0xf bound_ctrl:1
	s_nop 1
	v_add_f32_dpp v190, v190, v190 row_shr:4 row_mask:0xf bank_mask:0xf bound_ctrl:1
	s_nop 1
	v_add_f32_dpp v194, v190, v190 row_shr:8 row_mask:0xf bank_mask:0xf bound_ctrl:1
	ds_bpermute_b32 v190, v162, v194
	v_mul_f32_e32 v193, 0x3f317218, v193
	s_nop 1
	v_add_f32_dpp v193, v193, v193 row_shr:1 row_mask:0xf bank_mask:0xf bound_ctrl:1
	s_nop 1
	v_add_f32_dpp v193, v193, v193 row_shr:2 row_mask:0xf bank_mask:0xf bound_ctrl:1
	s_nop 1
	v_add_f32_dpp v193, v193, v193 row_shr:4 row_mask:0xf bank_mask:0xf bound_ctrl:1
	s_nop 1
	v_add_f32_dpp v193, v193, v193 row_shr:8 row_mask:0xf bank_mask:0xf bound_ctrl:1
	s_waitcnt lgkmcnt(0)
; __device__ __forceinline__ unsigned cvt_pk_bf16(float lo, float hi) { unsigned r; asm volatile("v_cvt_pk_bf16_f32 %0, %1, %2" : "=v"(r) : "v"(lo), "v"(hi)); return r; }
; __device__ __forceinline__ float row_scan16(float v) { v += dpp_shr0<0x111>(v); v += dpp_shr0<0x112>(v); v += dpp_shr0<0x114>(v); v += dpp_shr0<0x118>(v); return v; }
; __device__ __forceinline__ float row_last16(float v, int lane) { return __builtin_bit_cast(float, __builtin_amdgcn_ds_bpermute((lane | 15) << 2, __builtin_bit_cast(int, v))); }
;     __device__ __forceinline__ void operator()(const f32x4 (&acc)[2][2][4][2], const Unit& u, int wr, int wc, int fr, int fq) const {
;     ...
;                 for (int n = 0; n < 2; ++n)
; #pragma unroll
;                     for (int q = 0; q < 4; ++q) { const int j = 4 * n + q;
;                         const float k0 = om[n][q] / (1.0f + __expf(acc[ai][1][2 * mp][n][q])), k1 = om[n][q] / (1.0f + __expf(acc[ai][1][2 * mp + 1][n][q]));
;                         const float p0 = row_scan16(__logf(1.0f - k0)); const float t0 = row_last16(p0, lane);
;                         const float p1 = row_scan16(__logf(1.0f - k1)) + t0; const float bl = row_last16(p1, lane);
;                         const float e0 = __expf(p0), e1 = __expf(p1);
;                         qi[0][j] = acc[ai][0][2 * mp][n][q] * e0; qi[1][j] = acc[ai][0][2 * mp + 1][n][q] * e1;
;                         ki[0][j] = k0 * __expf(-p0); ki[1][j] = k1 * __expf(-p1);
;                         kot[(size_t)j * 32] = (bf16_t)cvt_pk_bf16(k0 * __expf(bl - p0), 0.f); kot[(size_t)j * 32 + 16] = (bf16_t)cvt_pk_bf16(k1 * __expf(bl - p1), 0.f);
;                         dec[j] = __expf(bl); }
	v_add_f32_e32 v193, v193, v190
	v_mul_f32_e32 v190, 0x3fb8aa3b, v194
	v_exp_f32_e32 v195, v190
	ds_bpermute_b32 v190, v162, v193
	v_mul_f32_e32 v196, 0x3fb8aa3b, v193
	v_mul_f32_e32 v198, 0xbfb8aa3b, v193
	v_mul_f32_e32 v197, v58, v195
	v_mul_f32_e32 v195, 0xbfb8aa3b, v194
	s_waitcnt lgkmcnt(0)
	v_sub_f32_e32 v194, v190, v194
	v_mul_f32_e32 v194, 0x3fb8aa3b, v194
	v_exp_f32_e32 v195, v195
	v_exp_f32_e32 v194, v194
	v_sub_f32_e32 v193, v190, v193
	v_mul_f32_e32 v193, 0x3fb8aa3b, v193
	v_mul_f32_e32 v203, v191, v195
	v_mul_f32_e32 v191, v191, v194
	v_cvt_pk_bf16_f32 v191, v191, v147
	global_store_short v[130:131], v191, off offset:256
	v_mul_f32_e32 v191, 0x3fb8aa3b, v43
	v_exp_f32_e32 v191, v191
	v_exp_f32_e32 v198, v198
	v_exp_f32_e32 v193, v193
	v_exp_f32_e32 v196, v196
	v_add_f32_e32 v191, 1.0, v191
	v_mul_f32_e32 v204, v192, v198
	v_mul_f32_e32 v192, v192, v193
	v_cvt_pk_bf16_f32 v192, v192, v147
	v_mul_f32_e32 v202, v46, v196
	global_store_short v[130:131], v192, off offset:288
	v_mul_f32_e32 v196, 0x3fb8aa3b, v27
	v_exp_f32_e32 v196, v196
	s_nop 0
	v_add_f32_e32 v194, 1.0, v196
	v_rcp_f32_e32 v192, v191
	s_nop 0
	v_mul_f32_e32 v192, v134, v192
	v_sub_f32_e32 v195, 1.0, v192
	v_log_f32_e32 v195, v195
	v_rcp_f32_e32 v191, v194
	s_nop 0
	v_mul_f32_e32 v193, v134, v191
	s_nop 1
	v_mul_f32_e32 v191, 0x3f317218, v195
	v_sub_f32_e32 v194, 1.0, v193
	s_nop 0
	v_add_f32_dpp v191, v191, v191 row_shr:1 row_mask:0xf bank_mask:0xf bound_ctrl:1
	s_nop 0
	v_log_f32_e32 v194, v194
	v_add_f32_dpp v191, v191, v191 row_shr:2 row_mask:0xf bank_mask:0xf bound_ctrl:1
	s_nop 1
	v_add_f32_dpp v191, v191, v191 row_shr:4 row_mask:0xf bank_mask:0xf bound_ctrl:1
	s_nop 1
	v_add_f32_dpp v195, v191, v191 row_shr:8 row_mask:0xf bank_mask:0xf bound_ctrl:1
	ds_bpermute_b32 v191, v162, v195
	v_mul_f32_e32 v194, 0x3f317218, v194
	v_mul_f32_e32 v199, 0xbfb8aa3b, v195
	v_exp_f32_e32 v199, v199
	v_add_f32_dpp v194, v194, v194 row_shr:1 row_mask:0xf bank_mask:0xf bound_ctrl:1
	v_mul_f32_e32 v206, v192, v199
	s_nop 0
	v_add_f32_dpp v194, v194, v194 row_shr:2 row_mask:0xf bank_mask:0xf bound_ctrl:1
	v_mul_f32_e32 v199, 0x3fb8aa3b, v28
	v_exp_f32_e32 v199, v199
	v_add_f32_dpp v194, v194, v194 row_shr:4 row_mask:0xf bank_mask:0xf bound_ctrl:1
	s_nop 1
	v_add_f32_dpp v194, v194, v194 row_shr:8 row_mask:0xf bank_mask:0xf bound_ctrl:1
	s_waitcnt lgkmcnt(0)
	v_add_f32_e32 v194, v194, v191
	v_mul_f32_e32 v191, 0x3fb8aa3b, v195
	v_exp_f32_e32 v196, v191
	ds_bpermute_b32 v191, v162, v194
	v_mul_f32_e32 v198, 0x3fb8aa3b, v194
	v_exp_f32_e32 v198, v198
	v_mul_f32_e32 v200, 0xbfb8aa3b, v194
	v_exp_f32_e32 v200, v200
	s_waitcnt lgkmcnt(0)
	v_sub_f32_e32 v195, v191, v195
	v_mul_f32_e32 v195, 0x3fb8aa3b, v195
	v_exp_f32_e32 v195, v195
	v_sub_f32_e32 v194, v191, v194
	v_mul_f32_e32 v194, 0x3fb8aa3b, v194
	v_exp_f32_e32 v194, v194
	v_mul_f32_e32 v192, v192, v195
	v_cvt_pk_bf16_f32 v192, v192, v147
	global_store_short v[130:131], v192, off offset:320
	v_mul_f32_e32 v192, 0x3fb8aa3b, v44
	v_exp_f32_e32 v192, v192
	v_mul_f32_e32 v205, v47, v198
	v_mul_f32_e32 v207, v193, v200
	v_mul_f32_e32 v193, v193, v194
	v_add_f32_e32 v192, 1.0, v192
	v_cvt_pk_bf16_f32 v193, v193, v147
	global_store_short v[130:131], v193, off offset:352
	v_mul_f32_e32 v196, v59, v196
	v_add_f32_e32 v195, 1.0, v199
	v_rcp_f32_e32 v193, v192
	s_nop 0
	v_mul_f32_e32 v193, v132, v193
	v_sub_f32_e32 v198, 1.0, v193
	v_log_f32_e32 v198, v198
	v_rcp_f32_e32 v192, v195
	s_nop 0
	v_mul_f32_e32 v194, v132, v192
	s_nop 1
	v_mul_f32_e32 v192, 0x3f317218, v198
	v_sub_f32_e32 v195, 1.0, v194
	s_nop 0
	v_add_f32_dpp v192, v192, v192 row_shr:1 row_mask:0xf bank_mask:0xf bound_ctrl:1
	s_nop 0
	v_log_f32_e32 v195, v195
	v_add_f32_dpp v192, v192, v192 row_shr:2 row_mask:0xf bank_mask:0xf bound_ctrl:1
	s_nop 1
	v_add_f32_dpp v192, v192, v192 row_shr:4 row_mask:0xf bank_mask:0xf bound_ctrl:1
	s_nop 1
	v_add_f32_dpp v198, v192, v192 row_shr:8 row_mask:0xf bank_mask:0xf bound_ctrl:1
	ds_bpermute_b32 v192, v162, v198
	v_mul_f32_e32 v195, 0x3f317218, v195
	s_nop 1
	v_add_f32_dpp v195, v195, v195 row_shr:1 row_mask:0xf bank_mask:0xf bound_ctrl:1
	s_nop 1
	v_add_f32_dpp v195, v195, v195 row_shr:2 row_mask:0xf bank_mask:0xf bound_ctrl:1
	s_nop 1
	v_add_f32_dpp v195, v195, v195 row_shr:4 row_mask:0xf bank_mask:0xf bound_ctrl:1
	s_nop 1
	v_add_f32_dpp v195, v195, v195 row_shr:8 row_mask:0xf bank_mask:0xf bound_ctrl:1
	s_waitcnt lgkmcnt(0)
	v_add_f32_e32 v195, v195, v192
	v_mul_f32_e32 v192, 0x3fb8aa3b, v198
	v_exp_f32_e32 v199, v192
	ds_bpermute_b32 v192, v162, v195
	v_mul_f32_e32 v200, 0x3fb8aa3b, v195
	v_mul_f32_e32 v208, 0xbfb8aa3b, v195
	v_mul_f32_e32 v201, v60, v199
	v_mul_f32_e32 v199, 0xbfb8aa3b, v198
	s_waitcnt lgkmcnt(0)
; __device__ __forceinline__ unsigned cvt_pk_bf16(float lo, float hi) { unsigned r; asm volatile("v_cvt_pk_bf16_f32 %0, %1, %2" : "=v"(r) : "v"(lo), "v"(hi)); return r; }
; __device__ __forceinline__ float row_scan16(float v) { v += dpp_shr0<0x111>(v); v += dpp_shr0<0x112>(v); v += dpp_shr0<0x114>(v); v += dpp_shr0<0x118>(v); return v; }
; __device__ __forceinline__ float row_last16(float v, int lane) { return __builtin_bit_cast(float, __builtin_amdgcn_ds_bpermute((lane | 15) << 2, __builtin_bit_cast(int, v))); }
;     __device__ __forceinline__ void operator()(const f32x4 (&acc)[2][2][4][2], const Unit& u, int wr, int wc, int fr, int fq) const {
;     ...
;                         const float k0 = om[n][q] / (1.0f + __expf(acc[ai][1][2 * mp][n][q])), k1 = om[n][q] / (1.0f + __expf(acc[ai][1][2 * mp + 1][n][q]));
;                         const float p0 = row_scan16(__logf(1.0f - k0)); const float t0 = row_last16(p0, lane);
;                         const float p1 = row_scan16(__logf(1.0f - k1)) + t0; const float bl = row_last16(p1, lane);
;                         const float e0 = __expf(p0), e1 = __expf(p1);
;                         qi[0][j] = acc[ai][0][2 * mp][n][q] * e0; qi[1][j] = acc[ai][0][2 * mp + 1][n][q] * e1;
;                         ki[0][j] = k0 * __expf(-p0); ki[1][j] = k1 * __expf(-p1);
;                         kot[(size_t)j * 32] = (bf16_t)cvt_pk_bf16(k0 * __expf(bl - p0), 0.f); kot[(size_t)j * 32 + 16] = (bf16_t)cvt_pk_bf16(k1 * __expf(bl - p1), 0.f);
;                         dec[j] = __expf(bl); }
; #pragma unroll
;                 for (int mm = 0; mm < 2; ++mm) { const size_t ro = (size_t)(rowa + 16 * mm) * 1024 + colh;
;                     u32x4 w; w.x = cvt_pk_bf16(qi[mm][0], qi[mm][1]); w.y = cvt_pk_bf16(qi[mm][2], qi[mm][3]); w.z = cvt_pk_bf16(qi[mm][4], qi[mm][5]); w.w = cvt_pk_bf16(qi[mm][6], qi[mm][7]);
;                     *(u32x4*)(CQ + ro) = w;
;                     w.x = cvt_pk_bf16(ki[mm][0], ki[mm][1]); w.y = cvt_pk_bf16(ki[mm][2], ki[mm][3]); w.z = cvt_pk_bf16(ki[mm][4], ki[mm][5]); w.w = cvt_pk_bf16(ki[mm][6], ki[mm][7]);
;                     *(u32x4*)(CK + ro) = w; }
;                 if (fr == 15) { float* dp = DEC + (size_t)g * 1024 + colh; *(f32x4*)dp = (f32x4){dec[0], dec[1], dec[2], dec[3]}; *(f32x4*)(dp + 4) = (f32x4){dec[4], dec[5], dec[6], dec[7]}; }
	v_sub_f32_e32 v198, v192, v198
	v_mul_f32_e32 v198, 0x3fb8aa3b, v198
	v_exp_f32_e32 v199, v199
	v_exp_f32_e32 v198, v198
	v_sub_f32_e32 v195, v192, v195
	v_mul_f32_e32 v195, 0x3fb8aa3b, v195
	v_mul_f32_e32 v210, v193, v199
	v_mul_f32_e32 v193, v193, v198
	v_cvt_pk_bf16_f32 v193, v193, v147
	global_store_short v[130:131], v193, off offset:384
	v_mul_f32_e32 v193, 0x3fb8aa3b, v45
	v_exp_f32_e32 v193, v193
	v_exp_f32_e32 v208, v208
	v_exp_f32_e32 v195, v195
	v_exp_f32_e32 v200, v200
	v_add_f32_e32 v193, 1.0, v193
	v_mul_f32_e32 v208, v194, v208
	v_mul_f32_e32 v194, v194, v195
	v_cvt_pk_bf16_f32 v194, v194, v147
	v_mul_f32_e32 v209, v48, v200
	global_store_short v[130:131], v194, off offset:416
	v_mul_f32_e32 v200, 0x3fb8aa3b, v29
	v_exp_f32_e32 v200, v200
	s_nop 0
	v_add_f32_e32 v198, 1.0, v200
	v_rcp_f32_e32 v194, v193
	s_nop 0
	v_mul_f32_e32 v194, v133, v194
	v_sub_f32_e32 v199, 1.0, v194
	v_log_f32_e32 v199, v199
	v_rcp_f32_e32 v193, v198
	s_nop 0
	v_mul_f32_e32 v195, v133, v193
	s_nop 1
	v_mul_f32_e32 v193, 0x3f317218, v199
	v_sub_f32_e32 v198, 1.0, v195
	s_nop 0
	v_add_f32_dpp v193, v193, v193 row_shr:1 row_mask:0xf bank_mask:0xf bound_ctrl:1
	s_nop 0
	v_log_f32_e32 v198, v198
	v_add_f32_dpp v193, v193, v193 row_shr:2 row_mask:0xf bank_mask:0xf bound_ctrl:1
	s_nop 1
	v_add_f32_dpp v193, v193, v193 row_shr:4 row_mask:0xf bank_mask:0xf bound_ctrl:1
	s_nop 1
	v_add_f32_dpp v199, v193, v193 row_shr:8 row_mask:0xf bank_mask:0xf bound_ctrl:1
	ds_bpermute_b32 v193, v162, v199
	v_mul_f32_e32 v198, 0x3f317218, v198
	v_mul_f32_e32 v200, 0x3fb8aa3b, v199
	v_mul_f32_e32 v212, 0xbfb8aa3b, v199
	v_add_f32_dpp v198, v198, v198 row_shr:1 row_mask:0xf bank_mask:0xf bound_ctrl:1
	v_exp_f32_e32 v212, v212
	v_exp_f32_e32 v200, v200
	v_add_f32_dpp v198, v198, v198 row_shr:2 row_mask:0xf bank_mask:0xf bound_ctrl:1
	v_mul_f32_e32 v212, v194, v212
	s_nop 0
	v_add_f32_dpp v198, v198, v198 row_shr:4 row_mask:0xf bank_mask:0xf bound_ctrl:1
	v_mul_f32_e32 v200, v61, v200
	s_nop 0
	v_add_f32_dpp v198, v198, v198 row_shr:8 row_mask:0xf bank_mask:0xf bound_ctrl:1
	s_waitcnt lgkmcnt(0)
	v_add_f32_e32 v198, v198, v193
	ds_bpermute_b32 v193, v162, v198
	v_mul_f32_e32 v211, 0x3fb8aa3b, v198
	v_mul_f32_e32 v213, 0xbfb8aa3b, v198
	v_exp_f32_e32 v213, v213
	v_exp_f32_e32 v211, v211
	s_waitcnt lgkmcnt(0)
	v_sub_f32_e32 v199, v193, v199
	v_mul_f32_e32 v199, 0x3fb8aa3b, v199
	v_exp_f32_e32 v199, v199
	v_sub_f32_e32 v198, v193, v198
	v_mul_f32_e32 v198, 0x3fb8aa3b, v198
	v_exp_f32_e32 v198, v198
	v_mul_f32_e32 v194, v194, v199
	v_cvt_pk_bf16_f32 v194, v194, v147
	global_store_short v[130:131], v194, off offset:448
	v_mul_f32_e32 v194, v195, v198
	v_cvt_pk_bf16_f32 v194, v194, v147
	global_store_short v[130:131], v194, off offset:480
	v_or_b32_e32 v130, s3, v1
	v_ashrrev_i32_e32 v131, 31, v130
	v_mul_f32_e32 v213, v195, v213
	v_lshlrev_b64 v[194:195], 10, v[130:131]
	v_or_b32_e32 v130, 16, v130
	v_lshl_add_u64 v[198:199], v[194:195], 0, v[158:159]
	v_ashrrev_i32_e32 v131, 31, v130
	v_lshlrev_b64 v[198:199], 1, v[198:199]
	v_lshlrev_b64 v[130:131], 10, v[130:131]
	v_cvt_pk_bf16_f32 v194, v172, v177
	v_cvt_pk_bf16_f32 v195, v182, v188
	v_cvt_pk_bf16_f32 v196, v197, v196
	v_cvt_pk_bf16_f32 v197, v201, v200
	v_lshl_add_u64 v[200:201], s[64:65], 0, v[198:199]
	v_lshl_add_u64 v[130:131], v[130:131], 0, v[158:159]
	global_store_dwordx4 v[200:201], v[194:197], off
	v_lshlrev_b64 v[130:131], 1, v[130:131]
	v_mul_f32_e32 v211, v49, v211
	v_cvt_pk_bf16_f32 v194, v173, v178
	v_cvt_pk_bf16_f32 v195, v183, v189
	v_cvt_pk_bf16_f32 v196, v203, v206
	v_cvt_pk_bf16_f32 v197, v210, v212
	v_lshl_add_u64 v[172:173], s[14:15], 0, v[198:199]
	global_store_dwordx4 v[172:173], v[194:197], off
	s_nop 1
	v_lshl_add_u64 v[172:173], s[64:65], 0, v[130:131]
	v_lshl_add_u64 v[130:131], s[14:15], 0, v[130:131]
	v_cvt_pk_bf16_f32 v194, v171, v176
	v_cvt_pk_bf16_f32 v195, v181, v187
	v_cvt_pk_bf16_f32 v196, v202, v205
	v_cvt_pk_bf16_f32 v197, v209, v211
	global_store_dwordx4 v[172:173], v[194:197], off
	s_nop 1
	v_cvt_pk_bf16_f32 v194, v161, v175
	v_cvt_pk_bf16_f32 v195, v180, v185
	v_cvt_pk_bf16_f32 v196, v204, v207
	v_cvt_pk_bf16_f32 v197, v208, v213
	global_store_dwordx4 v[130:131], v[194:197], off
	s_and_saveexec_b64 s[0:1], s[4:5]
	s_cbranch_execz .LBB0_1151
	v_mul_f32_e32 v130, 0x3fb8aa3b, v193
	v_exp_f32_e32 v183, v130
	v_mul_f32_e32 v130, 0x3fb8aa3b, v192
	v_exp_f32_e32 v182, v130
	v_mul_f32_e32 v130, 0x3fb8aa3b, v191
	v_exp_f32_e32 v181, v130
	v_mul_f32_e32 v130, 0x3fb8aa3b, v190
	v_exp_f32_e32 v180, v130
	v_mul_f32_e32 v130, 0x3fb8aa3b, v184
	v_exp_f32_e32 v177, v130
	v_mul_f32_e32 v130, 0x3fb8aa3b, v179
	v_exp_f32_e32 v176, v130
	v_mul_f32_e32 v130, 0x3fb8aa3b, v174
	v_exp_f32_e32 v175, v130
	v_mul_f32_e32 v130, 0x3fb8aa3b, v160
	v_exp_f32_e32 v174, v130
	s_lshl_b64 s[8:9], s[8:9], 2
	s_add_u32 s8, s47, s8
	s_addc_u32 s9, s52, s9
	v_lshl_add_u64 v[130:131], v[158:159], 2, s[8:9]
	global_store_dwordx4 v[130:131], v[174:177], off
	global_store_dwordx4 v[130:131], v[180:183], off offset:16
; __device__ __forceinline__ unsigned cvt_pk_bf16(float lo, float hi) { unsigned r; asm volatile("v_cvt_pk_bf16_f32 %0, %1, %2" : "=v"(r) : "v"(lo), "v"(hi)); return r; }
; __device__ __forceinline__ float row_scan16(float v) { v += dpp_shr0<0x111>(v); v += dpp_shr0<0x112>(v); v += dpp_shr0<0x114>(v); v += dpp_shr0<0x118>(v); return v; }
; __device__ __forceinline__ float row_last16(float v, int lane) { return __builtin_bit_cast(float, __builtin_amdgcn_ds_bpermute((lane | 15) << 2, __builtin_bit_cast(int, v))); }
;     __device__ __forceinline__ void operator()(const f32x4 (&acc)[2][2][4][2], const Unit& u, int wr, int wc, int fr, int fq) const {
;     ...
;                     for (int q = 0; q < 4; ++q) { const int j = 4 * n + q;
;                         const float k0 = om[n][q] / (1.0f + __expf(acc[ai][1][2 * mp][n][q])), k1 = om[n][q] / (1.0f + __expf(acc[ai][1][2 * mp + 1][n][q]));
;                         const float p0 = row_scan16(__logf(1.0f - k0)); const float t0 = row_last16(p0, lane);
;                         const float p1 = row_scan16(__logf(1.0f - k1)) + t0; const float bl = row_last16(p1, lane);
;                         const float e0 = __expf(p0), e1 = __expf(p1);
;                         qi[0][j] = acc[ai][0][2 * mp][n][q] * e0; qi[1][j] = acc[ai][0][2 * mp + 1][n][q] * e1;
;                         ki[0][j] = k0 * __expf(-p0); ki[1][j] = k1 * __expf(-p1);
;                         kot[(size_t)j * 32] = (bf16_t)cvt_pk_bf16(k0 * __expf(bl - p0), 0.f); kot[(size_t)j * 32 + 16] = (bf16_t)cvt_pk_bf16(k1 * __expf(bl - p1), 0.f);
;                         dec[j] = __expf(bl); }
.LBB0_1151:
	s_or_b64 exec, exec, s[0:1]
	v_mul_f32_e32 v130, 0x3fb8aa3b, v18
	v_exp_f32_e32 v130, v130
	s_addk_i32 s2, 0xa0
	s_ashr_i32 s0, s2, 5
	s_ashr_i32 s1, s0, 31
	v_add_f32_e32 v160, 1.0, v130
	s_lshl_b64 s[8:9], s[0:1], 10
	v_mul_f32_e32 v174, 0x3fb8aa3b, v6
	v_exp_f32_e32 v174, v174
	v_lshl_add_u64 v[130:131], s[8:9], 0, v[158:159]
	v_add_f32_e32 v172, 1.0, v174
	v_rcp_f32_e32 v161, v160
	s_nop 0
	v_mul_f32_e32 v173, v170, v161
	v_lshlrev_b64 v[130:131], 6, v[130:131]
	v_sub_f32_e32 v171, 1.0, v173
	v_log_f32_e32 v171, v171
	v_rcp_f32_e32 v160, v172
	s_nop 0
	v_mul_f32_e32 v174, v170, v160
	v_lshl_add_u64 v[130:131], v[148:149], 0, v[130:131]
	v_mul_f32_e32 v178, 0x3fb8aa3b, v7
	v_exp_f32_e32 v178, v178
	v_mul_f32_e32 v160, 0x3f317218, v171
	v_sub_f32_e32 v161, 1.0, v174
	s_nop 0
	v_add_f32_dpp v160, v160, v160 row_shr:1 row_mask:0xf bank_mask:0xf bound_ctrl:1
	v_mul_f32_e32 v182, 0x3fb8aa3b, v8
	v_log_f32_e32 v161, v161
	v_add_f32_dpp v160, v160, v160 row_shr:2 row_mask:0xf bank_mask:0xf bound_ctrl:1
	v_exp_f32_e32 v182, v182
	v_mul_f32_e32 v187, 0x3fb8aa3b, v9
	v_add_f32_dpp v160, v160, v160 row_shr:4 row_mask:0xf bank_mask:0xf bound_ctrl:1
	s_nop 1
	v_add_f32_dpp v170, v160, v160 row_shr:8 row_mask:0xf bank_mask:0xf bound_ctrl:1
	ds_bpermute_b32 v160, v162, v170
	v_mul_f32_e32 v161, 0x3f317218, v161
	v_exp_f32_e32 v187, v187
	v_mul_f32_e32 v191, 0x3fb8aa3b, v2
	v_add_f32_dpp v161, v161, v161 row_shr:1 row_mask:0xf bank_mask:0xf bound_ctrl:1
	v_exp_f32_e32 v191, v191
	s_nop 0
	v_add_f32_dpp v161, v161, v161 row_shr:2 row_mask:0xf bank_mask:0xf bound_ctrl:1
	s_nop 1
	v_add_f32_dpp v161, v161, v161 row_shr:4 row_mask:0xf bank_mask:0xf bound_ctrl:1
	s_nop 1
	v_add_f32_dpp v161, v161, v161 row_shr:8 row_mask:0xf bank_mask:0xf bound_ctrl:1
	s_waitcnt lgkmcnt(0)
	v_add_f32_e32 v175, v161, v160
	v_mul_f32_e32 v160, 0x3fb8aa3b, v170
	v_exp_f32_e32 v161, v160
	ds_bpermute_b32 v160, v162, v175
	v_mul_f32_e32 v171, 0x3fb8aa3b, v175
	v_exp_f32_e32 v172, v171
	v_mul_f32_e32 v171, v38, v161
	v_mul_f32_e32 v161, 0xbfb8aa3b, v170
	s_waitcnt lgkmcnt(0)
	v_sub_f32_e32 v170, v160, v170
	v_mul_f32_e32 v170, 0x3fb8aa3b, v170
	v_exp_f32_e32 v161, v161
	v_exp_f32_e32 v177, v170
	v_mul_f32_e32 v170, v22, v172
	v_mul_f32_e32 v176, 0xbfb8aa3b, v175
	v_mul_f32_e32 v172, v173, v161
	v_mul_f32_e32 v173, v173, v177
	v_cvt_pk_bf16_f32 v173, v173, v147
	global_store_short v[130:131], v173, off
	v_mul_f32_e32 v173, 0x3fb8aa3b, v19
	v_exp_f32_e32 v173, v173
	v_exp_f32_e32 v176, v176
	v_sub_f32_e32 v175, v160, v175
	v_mul_f32_e32 v175, 0x3fb8aa3b, v175
	v_exp_f32_e32 v175, v175
	v_add_f32_e32 v173, 1.0, v173
	v_mul_f32_e32 v161, v174, v176
	v_mul_f32_e32 v174, v174, v175
	v_cvt_pk_bf16_f32 v174, v174, v147
	global_store_short v[130:131], v174, off offset:32
	v_add_f32_e32 v176, 1.0, v178
	v_rcp_f32_e32 v174, v173
	s_nop 0
	v_mul_f32_e32 v177, v146, v174
	v_sub_f32_e32 v175, 1.0, v177
	v_log_f32_e32 v175, v175
	v_rcp_f32_e32 v173, v176
	s_nop 0
	v_mul_f32_e32 v178, v146, v173
	s_nop 1
	v_mul_f32_e32 v146, 0x3f317218, v175
	v_sub_f32_e32 v173, 1.0, v178
	s_nop 0
	v_add_f32_dpp v146, v146, v146 row_shr:1 row_mask:0xf bank_mask:0xf bound_ctrl:1
	s_nop 0
	v_log_f32_e32 v173, v173
	v_add_f32_dpp v146, v146, v146 row_shr:2 row_mask:0xf bank_mask:0xf bound_ctrl:1
	s_nop 1
	v_add_f32_dpp v146, v146, v146 row_shr:4 row_mask:0xf bank_mask:0xf bound_ctrl:1
	s_nop 1
	v_add_f32_dpp v174, v146, v146 row_shr:8 row_mask:0xf bank_mask:0xf bound_ctrl:1
	ds_bpermute_b32 v146, v162, v174
	v_mul_f32_e32 v173, 0x3f317218, v173
	s_nop 1
	v_add_f32_dpp v173, v173, v173 row_shr:1 row_mask:0xf bank_mask:0xf bound_ctrl:1
	s_nop 1
	v_add_f32_dpp v173, v173, v173 row_shr:2 row_mask:0xf bank_mask:0xf bound_ctrl:1
	s_nop 1
	v_add_f32_dpp v173, v173, v173 row_shr:4 row_mask:0xf bank_mask:0xf bound_ctrl:1
	s_nop 1
	v_add_f32_dpp v173, v173, v173 row_shr:8 row_mask:0xf bank_mask:0xf bound_ctrl:1
	s_waitcnt lgkmcnt(0)
	v_add_f32_e32 v179, v173, v146
	v_mul_f32_e32 v146, 0x3fb8aa3b, v174
	v_exp_f32_e32 v173, v146
	ds_bpermute_b32 v146, v162, v179
	v_mul_f32_e32 v175, 0x3fb8aa3b, v179
	v_exp_f32_e32 v176, v175
	v_mul_f32_e32 v175, v39, v173
	v_mul_f32_e32 v173, 0xbfb8aa3b, v174
	s_waitcnt lgkmcnt(0)
	v_sub_f32_e32 v174, v146, v174
	v_mul_f32_e32 v174, 0x3fb8aa3b, v174
	v_exp_f32_e32 v173, v173
	v_exp_f32_e32 v181, v174
	v_mul_f32_e32 v174, v23, v176
	v_mul_f32_e32 v180, 0xbfb8aa3b, v179
	v_mul_f32_e32 v176, v177, v173
	v_mul_f32_e32 v177, v177, v181
	v_cvt_pk_bf16_f32 v177, v177, v147
	global_store_short v[130:131], v177, off offset:64
	v_mul_f32_e32 v177, 0x3fb8aa3b, v20
	v_exp_f32_e32 v177, v177
	v_exp_f32_e32 v180, v180
	v_sub_f32_e32 v179, v146, v179
	v_mul_f32_e32 v179, 0x3fb8aa3b, v179
	v_exp_f32_e32 v179, v179
	v_add_f32_e32 v177, 1.0, v177
	v_mul_f32_e32 v173, v178, v180
	v_mul_f32_e32 v178, v178, v179
	v_cvt_pk_bf16_f32 v178, v178, v147
	global_store_short v[130:131], v178, off offset:96
	v_add_f32_e32 v180, 1.0, v182
	v_rcp_f32_e32 v178, v177
	s_nop 0
	v_mul_f32_e32 v181, v136, v178
	v_sub_f32_e32 v179, 1.0, v181
	v_log_f32_e32 v179, v179
	v_rcp_f32_e32 v177, v180
	s_nop 0
	v_mul_f32_e32 v182, v136, v177
	s_nop 1
	v_mul_f32_e32 v136, 0x3f317218, v179
	v_sub_f32_e32 v177, 1.0, v182
	s_nop 0
	v_add_f32_dpp v136, v136, v136 row_shr:1 row_mask:0xf bank_mask:0xf bound_ctrl:1
	s_nop 0
	v_log_f32_e32 v177, v177
	v_add_f32_dpp v136, v136, v136 row_shr:2 row_mask:0xf bank_mask:0xf bound_ctrl:1
	s_nop 1
	v_add_f32_dpp v136, v136, v136 row_shr:4 row_mask:0xf bank_mask:0xf bound_ctrl:1
	s_nop 1
	v_add_f32_dpp v178, v136, v136 row_shr:8 row_mask:0xf bank_mask:0xf bound_ctrl:1
	ds_bpermute_b32 v136, v162, v178
	v_mul_f32_e32 v177, 0x3f317218, v177
	s_nop 1
	v_add_f32_dpp v177, v177, v177 row_shr:1 row_mask:0xf bank_mask:0xf bound_ctrl:1
	s_nop 1
	v_add_f32_dpp v177, v177, v177 row_shr:2 row_mask:0xf bank_mask:0xf bound_ctrl:1
	s_nop 1
	v_add_f32_dpp v177, v177, v177 row_shr:4 row_mask:0xf bank_mask:0xf bound_ctrl:1
	s_nop 1
	v_add_f32_dpp v177, v177, v177 row_shr:8 row_mask:0xf bank_mask:0xf bound_ctrl:1
	s_waitcnt lgkmcnt(0)
; __device__ __forceinline__ unsigned cvt_pk_bf16(float lo, float hi) { unsigned r; asm volatile("v_cvt_pk_bf16_f32 %0, %1, %2" : "=v"(r) : "v"(lo), "v"(hi)); return r; }
; __device__ __forceinline__ float row_scan16(float v) { v += dpp_shr0<0x111>(v); v += dpp_shr0<0x112>(v); v += dpp_shr0<0x114>(v); v += dpp_shr0<0x118>(v); return v; }
; __device__ __forceinline__ float row_last16(float v, int lane) { return __builtin_bit_cast(float, __builtin_amdgcn_ds_bpermute((lane | 15) << 2, __builtin_bit_cast(int, v))); }
;     __device__ __forceinline__ void operator()(const f32x4 (&acc)[2][2][4][2], const Unit& u, int wr, int wc, int fr, int fq) const {
;     ...
;                     for (int q = 0; q < 4; ++q) { const int j = 4 * n + q;
;                         const float k0 = om[n][q] / (1.0f + __expf(acc[ai][1][2 * mp][n][q])), k1 = om[n][q] / (1.0f + __expf(acc[ai][1][2 * mp + 1][n][q]));
;                         const float p0 = row_scan16(__logf(1.0f - k0)); const float t0 = row_last16(p0, lane);
;                         const float p1 = row_scan16(__logf(1.0f - k1)) + t0; const float bl = row_last16(p1, lane);
;                         const float e0 = __expf(p0), e1 = __expf(p1);
;                         qi[0][j] = acc[ai][0][2 * mp][n][q] * e0; qi[1][j] = acc[ai][0][2 * mp + 1][n][q] * e1;
;                         ki[0][j] = k0 * __expf(-p0); ki[1][j] = k1 * __expf(-p1);
;                         kot[(size_t)j * 32] = (bf16_t)cvt_pk_bf16(k0 * __expf(bl - p0), 0.f); kot[(size_t)j * 32 + 16] = (bf16_t)cvt_pk_bf16(k1 * __expf(bl - p1), 0.f);
;                         dec[j] = __expf(bl); }
	v_add_f32_e32 v183, v177, v136
	v_mul_f32_e32 v136, 0x3fb8aa3b, v178
	v_exp_f32_e32 v177, v136
	ds_bpermute_b32 v136, v162, v183
	v_mul_f32_e32 v179, 0x3fb8aa3b, v183
	v_exp_f32_e32 v180, v179
	v_mul_f32_e32 v179, v40, v177
	v_mul_f32_e32 v177, 0xbfb8aa3b, v178
	s_waitcnt lgkmcnt(0)
	v_sub_f32_e32 v178, v136, v178
	v_mul_f32_e32 v178, 0x3fb8aa3b, v178
	v_exp_f32_e32 v177, v177
	v_exp_f32_e32 v185, v178
	v_mul_f32_e32 v178, v24, v180
	v_mul_f32_e32 v184, 0xbfb8aa3b, v183
	v_mul_f32_e32 v180, v181, v177
	v_mul_f32_e32 v181, v181, v185
	v_cvt_pk_bf16_f32 v181, v181, v147
	global_store_short v[130:131], v181, off offset:128
	v_mul_f32_e32 v181, 0x3fb8aa3b, v21
	v_exp_f32_e32 v181, v181
	v_exp_f32_e32 v184, v184
	v_sub_f32_e32 v183, v136, v183
	v_mul_f32_e32 v183, 0x3fb8aa3b, v183
	v_exp_f32_e32 v183, v183
	v_add_f32_e32 v181, 1.0, v181
	v_mul_f32_e32 v177, v182, v184
	v_mul_f32_e32 v182, v182, v183
	v_cvt_pk_bf16_f32 v182, v182, v147
	global_store_short v[130:131], v182, off offset:160
	v_add_f32_e32 v184, 1.0, v187
	v_rcp_f32_e32 v182, v181
	s_nop 0
	v_mul_f32_e32 v185, v137, v182
	v_sub_f32_e32 v183, 1.0, v185
	v_log_f32_e32 v183, v183
	v_rcp_f32_e32 v181, v184
	s_nop 0
	v_mul_f32_e32 v187, v137, v181
	s_nop 1
	v_mul_f32_e32 v137, 0x3f317218, v183
	v_sub_f32_e32 v181, 1.0, v187
	s_nop 0
	v_add_f32_dpp v137, v137, v137 row_shr:1 row_mask:0xf bank_mask:0xf bound_ctrl:1
	s_nop 0
	v_log_f32_e32 v181, v181
	v_add_f32_dpp v137, v137, v137 row_shr:2 row_mask:0xf bank_mask:0xf bound_ctrl:1
	s_nop 1
	v_add_f32_dpp v137, v137, v137 row_shr:4 row_mask:0xf bank_mask:0xf bound_ctrl:1
	s_nop 1
	v_add_f32_dpp v182, v137, v137 row_shr:8 row_mask:0xf bank_mask:0xf bound_ctrl:1
	ds_bpermute_b32 v137, v162, v182
	v_mul_f32_e32 v181, 0x3f317218, v181
	s_nop 1
	v_add_f32_dpp v181, v181, v181 row_shr:1 row_mask:0xf bank_mask:0xf bound_ctrl:1
	s_nop 1
	v_add_f32_dpp v181, v181, v181 row_shr:2 row_mask:0xf bank_mask:0xf bound_ctrl:1
	s_nop 1
	v_add_f32_dpp v181, v181, v181 row_shr:4 row_mask:0xf bank_mask:0xf bound_ctrl:1
	s_nop 1
	v_add_f32_dpp v181, v181, v181 row_shr:8 row_mask:0xf bank_mask:0xf bound_ctrl:1
	s_waitcnt lgkmcnt(0)
	v_add_f32_e32 v188, v181, v137
	v_mul_f32_e32 v137, 0x3fb8aa3b, v182
	v_exp_f32_e32 v181, v137
	ds_bpermute_b32 v137, v162, v188
	v_mul_f32_e32 v183, 0x3fb8aa3b, v188
	v_exp_f32_e32 v184, v183
	v_mul_f32_e32 v183, v41, v181
	v_mul_f32_e32 v181, 0xbfb8aa3b, v182
	s_waitcnt lgkmcnt(0)
	v_sub_f32_e32 v182, v137, v182
	v_mul_f32_e32 v182, 0x3fb8aa3b, v182
	v_exp_f32_e32 v181, v181
	v_exp_f32_e32 v190, v182
	v_mul_f32_e32 v182, v25, v184
	v_mul_f32_e32 v189, 0xbfb8aa3b, v188
	v_mul_f32_e32 v184, v185, v181
	v_mul_f32_e32 v185, v185, v190
	v_cvt_pk_bf16_f32 v185, v185, v147
	global_store_short v[130:131], v185, off offset:192
	v_mul_f32_e32 v185, 0x3fb8aa3b, v10
	v_exp_f32_e32 v185, v185
	v_exp_f32_e32 v189, v189
	v_sub_f32_e32 v188, v137, v188
	v_mul_f32_e32 v188, 0x3fb8aa3b, v188
	v_exp_f32_e32 v188, v188
	v_add_f32_e32 v185, 1.0, v185
	v_mul_f32_e32 v181, v187, v189
	v_mul_f32_e32 v187, v187, v188
	v_cvt_pk_bf16_f32 v187, v187, v147
	global_store_short v[130:131], v187, off offset:224
	v_add_f32_e32 v189, 1.0, v191
	v_rcp_f32_e32 v187, v185
	s_nop 0
	v_mul_f32_e32 v185, v135, v187
	v_sub_f32_e32 v190, 1.0, v185
	v_log_f32_e32 v190, v190
	v_rcp_f32_e32 v187, v189
	s_nop 0
	v_mul_f32_e32 v187, v135, v187
	s_nop 1
	v_mul_f32_e32 v135, 0x3f317218, v190
	v_sub_f32_e32 v188, 1.0, v187
	s_nop 0
	v_add_f32_dpp v135, v135, v135 row_shr:1 row_mask:0xf bank_mask:0xf bound_ctrl:1
	s_nop 0
	v_log_f32_e32 v188, v188
	v_add_f32_dpp v135, v135, v135 row_shr:2 row_mask:0xf bank_mask:0xf bound_ctrl:1
	s_nop 1
	v_add_f32_dpp v135, v135, v135 row_shr:4 row_mask:0xf bank_mask:0xf bound_ctrl:1
	s_nop 1
	v_add_f32_dpp v189, v135, v135 row_shr:8 row_mask:0xf bank_mask:0xf bound_ctrl:1
	ds_bpermute_b32 v135, v162, v189
	v_mul_f32_e32 v188, 0x3f317218, v188
	v_mul_f32_e32 v192, 0xbfb8aa3b, v189
	v_exp_f32_e32 v192, v192
	v_add_f32_dpp v188, v188, v188 row_shr:1 row_mask:0xf bank_mask:0xf bound_ctrl:1
	v_mul_f32_e32 v197, v185, v192
	s_nop 0
	v_add_f32_dpp v188, v188, v188 row_shr:2 row_mask:0xf bank_mask:0xf bound_ctrl:1
	v_mul_f32_e32 v192, 0x3fb8aa3b, v3
	v_exp_f32_e32 v192, v192
	v_add_f32_dpp v188, v188, v188 row_shr:4 row_mask:0xf bank_mask:0xf bound_ctrl:1
	s_nop 1
	v_add_f32_dpp v188, v188, v188 row_shr:8 row_mask:0xf bank_mask:0xf bound_ctrl:1
	s_waitcnt lgkmcnt(0)
	v_add_f32_e32 v188, v188, v135
	v_mul_f32_e32 v135, 0x3fb8aa3b, v189
	v_exp_f32_e32 v190, v135
	ds_bpermute_b32 v135, v162, v188
	v_mul_f32_e32 v191, 0x3fb8aa3b, v188
	v_exp_f32_e32 v191, v191
	v_mul_f32_e32 v193, 0xbfb8aa3b, v188
	v_exp_f32_e32 v193, v193
	s_waitcnt lgkmcnt(0)
; __device__ __forceinline__ unsigned cvt_pk_bf16(float lo, float hi) { unsigned r; asm volatile("v_cvt_pk_bf16_f32 %0, %1, %2" : "=v"(r) : "v"(lo), "v"(hi)); return r; }
; __device__ __forceinline__ float row_scan16(float v) { v += dpp_shr0<0x111>(v); v += dpp_shr0<0x112>(v); v += dpp_shr0<0x114>(v); v += dpp_shr0<0x118>(v); return v; }
; __device__ __forceinline__ float row_last16(float v, int lane) { return __builtin_bit_cast(float, __builtin_amdgcn_ds_bpermute((lane | 15) << 2, __builtin_bit_cast(int, v))); }
;     __device__ __forceinline__ void operator()(const f32x4 (&acc)[2][2][4][2], const Unit& u, int wr, int wc, int fr, int fq) const {
;     ...
;                     for (int q = 0; q < 4; ++q) { const int j = 4 * n + q;
;                         const float k0 = om[n][q] / (1.0f + __expf(acc[ai][1][2 * mp][n][q])), k1 = om[n][q] / (1.0f + __expf(acc[ai][1][2 * mp + 1][n][q]));
;                         const float p0 = row_scan16(__logf(1.0f - k0)); const float t0 = row_last16(p0, lane);
;                         const float p1 = row_scan16(__logf(1.0f - k1)) + t0; const float bl = row_last16(p1, lane);
;                         const float e0 = __expf(p0), e1 = __expf(p1);
;                         qi[0][j] = acc[ai][0][2 * mp][n][q] * e0; qi[1][j] = acc[ai][0][2 * mp + 1][n][q] * e1;
;                         ki[0][j] = k0 * __expf(-p0); ki[1][j] = k1 * __expf(-p1);
;                         kot[(size_t)j * 32] = (bf16_t)cvt_pk_bf16(k0 * __expf(bl - p0), 0.f); kot[(size_t)j * 32 + 16] = (bf16_t)cvt_pk_bf16(k1 * __expf(bl - p1), 0.f);
;                         dec[j] = __expf(bl); }
	v_sub_f32_e32 v189, v135, v189
	v_mul_f32_e32 v189, 0x3fb8aa3b, v189
	v_exp_f32_e32 v189, v189
	v_sub_f32_e32 v188, v135, v188
	v_mul_f32_e32 v188, 0x3fb8aa3b, v188
	v_exp_f32_e32 v188, v188
	v_mul_f32_e32 v185, v185, v189
	v_cvt_pk_bf16_f32 v185, v185, v147
	global_store_short v[130:131], v185, off offset:256
	v_mul_f32_e32 v185, 0x3fb8aa3b, v11
	v_exp_f32_e32 v185, v185
	v_mul_f32_e32 v196, v14, v191
	v_mul_f32_e32 v198, v187, v193
	v_mul_f32_e32 v187, v187, v188
	v_add_f32_e32 v185, 1.0, v185
	v_cvt_pk_bf16_f32 v187, v187, v147
	global_store_short v[130:131], v187, off offset:288
	v_mul_f32_e32 v190, v30, v190
	v_add_f32_e32 v189, 1.0, v192
	v_rcp_f32_e32 v187, v185
	s_nop 0
	v_mul_f32_e32 v185, v134, v187
	v_sub_f32_e32 v191, 1.0, v185
	v_log_f32_e32 v191, v191
	v_rcp_f32_e32 v187, v189
	s_nop 0
	v_mul_f32_e32 v187, v134, v187
	s_nop 1
	v_mul_f32_e32 v134, 0x3f317218, v191
	v_sub_f32_e32 v188, 1.0, v187
	s_nop 0
	v_add_f32_dpp v134, v134, v134 row_shr:1 row_mask:0xf bank_mask:0xf bound_ctrl:1
	s_nop 0
	v_log_f32_e32 v188, v188
	v_add_f32_dpp v134, v134, v134 row_shr:2 row_mask:0xf bank_mask:0xf bound_ctrl:1
	s_nop 1
	v_add_f32_dpp v134, v134, v134 row_shr:4 row_mask:0xf bank_mask:0xf bound_ctrl:1
	s_nop 1
	v_add_f32_dpp v189, v134, v134 row_shr:8 row_mask:0xf bank_mask:0xf bound_ctrl:1
	ds_bpermute_b32 v134, v162, v189
	v_mul_f32_e32 v188, 0x3f317218, v188
	v_mul_f32_e32 v193, 0xbfb8aa3b, v189
	v_exp_f32_e32 v193, v193
	v_add_f32_dpp v188, v188, v188 row_shr:1 row_mask:0xf bank_mask:0xf bound_ctrl:1
	v_mul_f32_e32 v200, v185, v193
	s_nop 0
	v_add_f32_dpp v188, v188, v188 row_shr:2 row_mask:0xf bank_mask:0xf bound_ctrl:1
	v_mul_f32_e32 v193, 0x3fb8aa3b, v4
	v_exp_f32_e32 v193, v193
	v_add_f32_dpp v188, v188, v188 row_shr:4 row_mask:0xf bank_mask:0xf bound_ctrl:1
	s_nop 1
	v_add_f32_dpp v188, v188, v188 row_shr:8 row_mask:0xf bank_mask:0xf bound_ctrl:1
	s_waitcnt lgkmcnt(0)
	v_add_f32_e32 v188, v188, v134
	v_mul_f32_e32 v134, 0x3fb8aa3b, v189
	v_exp_f32_e32 v191, v134
	ds_bpermute_b32 v134, v162, v188
	v_mul_f32_e32 v192, 0x3fb8aa3b, v188
	v_exp_f32_e32 v192, v192
	v_mul_f32_e32 v194, 0xbfb8aa3b, v188
	v_exp_f32_e32 v194, v194
	s_waitcnt lgkmcnt(0)
	v_sub_f32_e32 v189, v134, v189
	v_mul_f32_e32 v189, 0x3fb8aa3b, v189
	v_exp_f32_e32 v189, v189
	v_sub_f32_e32 v188, v134, v188
	v_mul_f32_e32 v188, 0x3fb8aa3b, v188
	v_exp_f32_e32 v188, v188
	v_mul_f32_e32 v185, v185, v189
	v_cvt_pk_bf16_f32 v185, v185, v147
	global_store_short v[130:131], v185, off offset:320
	v_mul_f32_e32 v185, 0x3fb8aa3b, v12
	v_exp_f32_e32 v185, v185
	v_mul_f32_e32 v199, v15, v192
	v_mul_f32_e32 v201, v187, v194
	v_mul_f32_e32 v187, v187, v188
	v_add_f32_e32 v185, 1.0, v185
	v_cvt_pk_bf16_f32 v187, v187, v147
	global_store_short v[130:131], v187, off offset:352
	v_mul_f32_e32 v191, v31, v191
	v_add_f32_e32 v189, 1.0, v193
	v_rcp_f32_e32 v187, v185
	s_nop 0
	v_mul_f32_e32 v185, v132, v187
	v_sub_f32_e32 v192, 1.0, v185
	v_log_f32_e32 v192, v192
	v_rcp_f32_e32 v187, v189
	s_nop 0
	v_mul_f32_e32 v187, v132, v187
	s_nop 1
	v_mul_f32_e32 v132, 0x3f317218, v192
	v_sub_f32_e32 v188, 1.0, v187
	s_nop 0
	v_add_f32_dpp v132, v132, v132 row_shr:1 row_mask:0xf bank_mask:0xf bound_ctrl:1
	s_nop 0
	v_log_f32_e32 v188, v188
	v_add_f32_dpp v132, v132, v132 row_shr:2 row_mask:0xf bank_mask:0xf bound_ctrl:1
	s_nop 1
	v_add_f32_dpp v132, v132, v132 row_shr:4 row_mask:0xf bank_mask:0xf bound_ctrl:1
	s_nop 1
	v_add_f32_dpp v189, v132, v132 row_shr:8 row_mask:0xf bank_mask:0xf bound_ctrl:1
	ds_bpermute_b32 v132, v162, v189
	v_mul_f32_e32 v188, 0x3f317218, v188
	s_nop 1
	v_add_f32_dpp v188, v188, v188 row_shr:1 row_mask:0xf bank_mask:0xf bound_ctrl:1
	s_nop 1
	v_add_f32_dpp v188, v188, v188 row_shr:2 row_mask:0xf bank_mask:0xf bound_ctrl:1
	s_nop 1
	v_add_f32_dpp v188, v188, v188 row_shr:4 row_mask:0xf bank_mask:0xf bound_ctrl:1
	s_nop 1
	v_add_f32_dpp v188, v188, v188 row_shr:8 row_mask:0xf bank_mask:0xf bound_ctrl:1
	s_waitcnt lgkmcnt(0)
	v_add_f32_e32 v188, v188, v132
	v_mul_f32_e32 v132, 0x3fb8aa3b, v189
	v_exp_f32_e32 v192, v132
	ds_bpermute_b32 v132, v162, v188
	v_mul_f32_e32 v193, 0x3fb8aa3b, v188
	v_mul_f32_e32 v195, 0xbfb8aa3b, v188
	v_mul_f32_e32 v194, v32, v192
	v_mul_f32_e32 v192, 0xbfb8aa3b, v189
	s_waitcnt lgkmcnt(0)
; __device__ __forceinline__ unsigned cvt_pk_bf16(float lo, float hi) { unsigned r; asm volatile("v_cvt_pk_bf16_f32 %0, %1, %2" : "=v"(r) : "v"(lo), "v"(hi)); return r; }
; __device__ __forceinline__ float row_scan16(float v) { v += dpp_shr0<0x111>(v); v += dpp_shr0<0x112>(v); v += dpp_shr0<0x114>(v); v += dpp_shr0<0x118>(v); return v; }
;     __device__ __forceinline__ void operator()(const f32x4 (&acc)[2][2][4][2], const Unit& u, int wr, int wc, int fr, int fq) const {
;     ...
;                     for (int q = 0; q < 4; ++q) { const int j = 4 * n + q;
;                         const float k0 = om[n][q] / (1.0f + __expf(acc[ai][1][2 * mp][n][q])), k1 = om[n][q] / (1.0f + __expf(acc[ai][1][2 * mp + 1][n][q]));
;                         const float p0 = row_scan16(__logf(1.0f - k0)); const float t0 = row_last16(p0, lane);
;                         const float p1 = row_scan16(__logf(1.0f - k1)) + t0; const float bl = row_last16(p1, lane);
;                         const float e0 = __expf(p0), e1 = __expf(p1);
;                         qi[0][j] = acc[ai][0][2 * mp][n][q] * e0; qi[1][j] = acc[ai][0][2 * mp + 1][n][q] * e1;
;                         ki[0][j] = k0 * __expf(-p0); ki[1][j] = k1 * __expf(-p1);
;                         kot[(size_t)j * 32] = (bf16_t)cvt_pk_bf16(k0 * __expf(bl - p0), 0.f); kot[(size_t)j * 32 + 16] = (bf16_t)cvt_pk_bf16(k1 * __expf(bl - p1), 0.f);
;                         dec[j] = __expf(bl); }
; #pragma unroll
;                 for (int mm = 0; mm < 2; ++mm) { const size_t ro = (size_t)(rowa + 16 * mm) * 1024 + colh;
;                     u32x4 w; w.x = cvt_pk_bf16(qi[mm][0], qi[mm][1]); w.y = cvt_pk_bf16(qi[mm][2], qi[mm][3]); w.z = cvt_pk_bf16(qi[mm][4], qi[mm][5]); w.w = cvt_pk_bf16(qi[mm][6], qi[mm][7]);
;                     *(u32x4*)(CQ + ro) = w;
;                     w.x = cvt_pk_bf16(ki[mm][0], ki[mm][1]); w.y = cvt_pk_bf16(ki[mm][2], ki[mm][3]); w.z = cvt_pk_bf16(ki[mm][4], ki[mm][5]); w.w = cvt_pk_bf16(ki[mm][6], ki[mm][7]);
;                     *(u32x4*)(CK + ro) = w; }
;                 if (fr == 15) { float* dp = DEC + (size_t)g * 1024 + colh; *(f32x4*)dp = (f32x4){dec[0], dec[1], dec[2], dec[3]}; *(f32x4*)(dp + 4) = (f32x4){dec[4], dec[5], dec[6], dec[7]}; }
	v_sub_f32_e32 v189, v132, v189
	v_mul_f32_e32 v189, 0x3fb8aa3b, v189
	v_exp_f32_e32 v192, v192
	v_exp_f32_e32 v189, v189
	v_sub_f32_e32 v188, v132, v188
	v_mul_f32_e32 v188, 0x3fb8aa3b, v188
	v_mul_f32_e32 v203, v185, v192
	v_mul_f32_e32 v185, v185, v189
	v_cvt_pk_bf16_f32 v185, v185, v147
	global_store_short v[130:131], v185, off offset:384
	v_mul_f32_e32 v185, 0x3fb8aa3b, v13
	v_exp_f32_e32 v185, v185
	v_exp_f32_e32 v195, v195
	v_exp_f32_e32 v188, v188
	v_exp_f32_e32 v193, v193
	v_add_f32_e32 v185, 1.0, v185
	v_mul_f32_e32 v204, v187, v195
	v_mul_f32_e32 v187, v187, v188
	v_cvt_pk_bf16_f32 v187, v187, v147
	v_mul_f32_e32 v202, v16, v193
	global_store_short v[130:131], v187, off offset:416
	v_mul_f32_e32 v193, 0x3fb8aa3b, v5
	v_exp_f32_e32 v193, v193
	s_nop 0
	v_add_f32_e32 v189, 1.0, v193
	v_rcp_f32_e32 v187, v185
	s_nop 0
	v_mul_f32_e32 v185, v133, v187
	v_sub_f32_e32 v192, 1.0, v185
	v_log_f32_e32 v192, v192
	v_rcp_f32_e32 v187, v189
	s_nop 0
	v_mul_f32_e32 v187, v133, v187
	s_nop 1
	v_mul_f32_e32 v133, 0x3f317218, v192
	v_sub_f32_e32 v188, 1.0, v187
	s_nop 0
	v_add_f32_dpp v133, v133, v133 row_shr:1 row_mask:0xf bank_mask:0xf bound_ctrl:1
	s_nop 0
	v_log_f32_e32 v188, v188
	v_add_f32_dpp v133, v133, v133 row_shr:2 row_mask:0xf bank_mask:0xf bound_ctrl:1
	s_nop 1
	v_add_f32_dpp v133, v133, v133 row_shr:4 row_mask:0xf bank_mask:0xf bound_ctrl:1
	s_nop 1
	v_add_f32_dpp v189, v133, v133 row_shr:8 row_mask:0xf bank_mask:0xf bound_ctrl:1
	ds_bpermute_b32 v133, v162, v189
	v_mul_f32_e32 v188, 0x3f317218, v188
	v_mul_f32_e32 v192, 0x3fb8aa3b, v189
	v_mul_f32_e32 v195, 0xbfb8aa3b, v189
	v_add_f32_dpp v188, v188, v188 row_shr:1 row_mask:0xf bank_mask:0xf bound_ctrl:1
	v_exp_f32_e32 v195, v195
	v_exp_f32_e32 v192, v192
	v_add_f32_dpp v188, v188, v188 row_shr:2 row_mask:0xf bank_mask:0xf bound_ctrl:1
	v_mul_f32_e32 v208, v185, v195
	s_nop 0
	v_add_f32_dpp v188, v188, v188 row_shr:4 row_mask:0xf bank_mask:0xf bound_ctrl:1
	v_mul_f32_e32 v206, v33, v192
	s_nop 0
	v_add_f32_dpp v188, v188, v188 row_shr:8 row_mask:0xf bank_mask:0xf bound_ctrl:1
	s_waitcnt lgkmcnt(0)
	v_add_f32_e32 v188, v188, v133
	ds_bpermute_b32 v133, v162, v188
	v_mul_f32_e32 v193, 0x3fb8aa3b, v188
	v_mul_f32_e32 v205, 0xbfb8aa3b, v188
	v_exp_f32_e32 v193, v193
	v_exp_f32_e32 v205, v205
	s_waitcnt lgkmcnt(0)
	v_sub_f32_e32 v189, v133, v189
	v_mul_f32_e32 v189, 0x3fb8aa3b, v189
	v_exp_f32_e32 v189, v189
	v_sub_f32_e32 v188, v133, v188
	v_mul_f32_e32 v188, 0x3fb8aa3b, v188
	v_exp_f32_e32 v188, v188
	v_mul_f32_e32 v185, v185, v189
	v_cvt_pk_bf16_f32 v185, v185, v147
	global_store_short v[130:131], v185, off offset:448
	v_mul_f32_e32 v185, v187, v188
	v_cvt_pk_bf16_f32 v185, v185, v147
	global_store_short v[130:131], v185, off offset:480
	v_or_b32_e32 v130, s2, v1
	v_ashrrev_i32_e32 v131, 31, v130
	v_lshlrev_b64 v[188:189], 10, v[130:131]
	v_or_b32_e32 v130, 16, v130
	v_mul_f32_e32 v207, v17, v193
	v_lshl_add_u64 v[192:193], v[188:189], 0, v[158:159]
	v_ashrrev_i32_e32 v131, 31, v130
	v_lshlrev_b64 v[192:193], 1, v[192:193]
	v_lshlrev_b64 v[130:131], 10, v[130:131]
	v_cvt_pk_bf16_f32 v188, v171, v175
	v_cvt_pk_bf16_f32 v189, v179, v183
	v_cvt_pk_bf16_f32 v190, v190, v191
	v_cvt_pk_bf16_f32 v191, v194, v206
	v_lshl_add_u64 v[194:195], s[64:65], 0, v[192:193]
	v_lshl_add_u64 v[130:131], v[130:131], 0, v[158:159]
	global_store_dwordx4 v[194:195], v[188:191], off
	v_lshlrev_b64 v[130:131], 1, v[130:131]
	v_mul_f32_e32 v205, v187, v205
	v_cvt_pk_bf16_f32 v188, v172, v176
	v_cvt_pk_bf16_f32 v189, v180, v184
	v_lshl_add_u64 v[184:185], s[14:15], 0, v[192:193]
	v_cvt_pk_bf16_f32 v190, v197, v200
	v_cvt_pk_bf16_f32 v191, v203, v208
	global_store_dwordx4 v[184:185], v[188:191], off
	s_nop 1
	v_cvt_pk_bf16_f32 v188, v170, v174
	v_lshl_add_u64 v[170:171], s[64:65], 0, v[130:131]
	v_lshl_add_u64 v[130:131], s[14:15], 0, v[130:131]
	v_cvt_pk_bf16_f32 v189, v178, v182
	v_cvt_pk_bf16_f32 v190, v196, v199
	v_cvt_pk_bf16_f32 v191, v202, v207
	global_store_dwordx4 v[170:171], v[188:191], off
	s_nop 1
	v_cvt_pk_bf16_f32 v170, v161, v173
	v_cvt_pk_bf16_f32 v171, v177, v181
	v_cvt_pk_bf16_f32 v172, v198, v201
	v_cvt_pk_bf16_f32 v173, v204, v205
	global_store_dwordx4 v[130:131], v[170:173], off
	s_and_saveexec_b64 s[0:1], s[4:5]
	s_cbranch_execz .LBB0_1153
	v_mul_f32_e32 v130, 0x3fb8aa3b, v133
	v_exp_f32_e32 v133, v130
	v_mul_f32_e32 v130, 0x3fb8aa3b, v132
	v_exp_f32_e32 v132, v130
	v_mul_f32_e32 v130, 0x3fb8aa3b, v134
	v_mul_f32_e32 v134, 0x3fb8aa3b, v137
	v_exp_f32_e32 v137, v134
	v_mul_f32_e32 v134, 0x3fb8aa3b, v136
	v_exp_f32_e32 v136, v134
	v_mul_f32_e32 v134, 0x3fb8aa3b, v146
	v_exp_f32_e32 v131, v130
	v_mul_f32_e32 v130, 0x3fb8aa3b, v135
	v_exp_f32_e32 v135, v134
	v_mul_f32_e32 v134, 0x3fb8aa3b, v160
	v_exp_f32_e32 v134, v134
	s_lshl_b64 s[2:3], s[8:9], 2
	v_exp_f32_e32 v130, v130
	s_add_u32 s2, s47, s2
	s_addc_u32 s3, s52, s3
	v_lshl_add_u64 v[158:159], v[158:159], 2, s[2:3]
	global_store_dwordx4 v[158:159], v[134:137], off
	global_store_dwordx4 v[158:159], v[130:133], off offset:16
